# scan: SSD/GLA step sequence rewritten straight-line (decays read 8 steps ahead, no per-step branches); ssd: dt-section loads merged, epilogue norm weights hoisted; s5_out u-tile prefetched at lru_out
# speedup vs baseline: 1.0203x; 1.0051x over previous
.LBB0_60:
	v_readlane_b32 s4, v250, 6
	v_readlane_b32 s5, v250, 7
	s_add_u32 s4, s4, s28
	s_mul_hi_i32 s3, s1, s20
	s_mul_i32 s2, s1, s20
	s_addc_u32 s5, s5, s29
	s_lshl_b64 s[2:3], s[2:3], 7
	s_add_u32 s88, s4, s2
	s_addc_u32 s1, s5, s3
	v_mov_b32_e32 v14, 0
	s_lshl_b32 s90, s20, 7
	s_and_b32 s89, s1, 0xffff
	v_lshl_add_u32 v20, s0, 11, v13
	s_mov_b32 s93, 0
	s_mov_b64 s[30:31], -1
	v_mov_b32_e32 v15, v14
	v_readlane_b32 s6, v250, 8
	v_readlane_b32 s7, v250, 9
	s_waitcnt lgkmcnt(0)
	s_barrier
	s_branch .LBB0_62
.LBB0_62:
	v_mov_b32_e32 v16, s20
	s_xor_b64 s[28:29], s[30:31], -1
	v_mul_u32_u24_e32 v18, s93, v16
	s_mov_b64 s[30:31], exec
	v_readlane_b32 s0, v250, 21
	v_readlane_b32 s0, v250, 22

.LBB0_65:
	v_readfirstlane_b32 s0, v27
	s_nop 1
	v_cmp_eq_u32_e32 vcc, s0, v27
	s_and_saveexec_b64 vcc, vcc
	s_nop 0
	buffer_load_dword v84, v20, s[88:91], s0 offen
	s_xor_b64 exec, exec, vcc
	s_cbranch_execnz .LBB0_65
	s_mov_b32 s75, s95
	s_mov_b32 s74, s92
	s_mov_b64 exec, s[30:31]
	v_readfirstlane_b32 s19, v27
	s_add_i32 s19, s19, s20
	s_add_i32 s18, s19, s20
	s_add_i32 s17, s18, s20
	s_add_i32 s16, s17, s20
	s_add_i32 s15, s16, s20
	s_add_i32 s14, s15, s20
	s_add_i32 s13, s14, s20
	s_add_i32 s12, s13, s20
	s_add_i32 s11, s12, s20
	s_add_i32 s10, s11, s20
	s_add_i32 s9, s10, s20
	s_add_i32 s8, s9, s20
	s_add_i32 s7, s8, s20
	s_add_i32 s6, s7, s20
	s_add_i32 s5, s6, s20
	s_add_i32 s1, s5, s20
	s_add_i32 s3, s1, s20
	s_add_i32 s23, s3, s20
	s_add_i32 s39, s23, s20
	s_add_i32 s37, s39, s20
	s_add_i32 s41, s37, s20
	s_add_i32 s43, s41, s20
	s_add_i32 s97, s43, s20
	s_add_i32 s96, s97, s20
	s_add_i32 s71, s96, s20
	s_add_i32 s70, s71, s20
	s_add_i32 s69, s70, s20
	s_add_i32 s68, s69, s20
	s_add_i32 s67, s68, s20
	s_add_i32 s66, s67, s20
	s_add_i32 s65, s66, s20
	s_add_i32 s64, s65, s20
	s_add_i32 s63, s64, s20
	s_add_i32 s62, s63, s20
	s_add_i32 s61, s62, s20
	s_add_i32 s60, s61, s20
	s_add_i32 s59, s60, s20
	s_add_i32 s58, s59, s20
	s_add_i32 s57, s58, s20
	s_add_i32 s56, s57, s20
	s_add_i32 s55, s56, s20
	s_add_i32 s54, s55, s20
	s_add_i32 s53, s54, s20
	s_add_i32 s52, s53, s20
	s_add_i32 s51, s52, s20
	s_add_i32 s50, s51, s20
	s_add_i32 s49, s50, s20
	s_add_i32 s35, s49, s20
	s_add_i32 s34, s35, s20
	s_add_i32 s42, s34, s20
	s_add_i32 s40, s42, s20
	s_add_i32 s36, s40, s20
	s_add_i32 s38, s36, s20
	s_add_i32 s22, s38, s20
	s_add_i32 s2, s22, s20
	s_add_i32 s0, s2, s20
	s_add_i32 s48, s0, s20
	s_add_i32 s46, s48, s20
	s_add_i32 s92, s46, s20
	s_add_i32 s95, s92, s20
	s_add_i32 s4, s95, s20
	s_add_i32 s26, s4, s20
	buffer_load_dword v83, v20, s[88:91], s19 offen
	buffer_load_dword v81, v20, s[88:91], s17 offen
	buffer_load_dword v80, v20, s[88:91], s16 offen
	buffer_load_dword v66, v20, s[88:91], s23 offen
	buffer_load_dword v35, v20, s[88:91], s34 offen
	buffer_load_dword v22, v20, s[88:91], s26 offen
	buffer_load_dword v30, v20, s[88:91], s22 offen
	buffer_load_dword v82, v20, s[88:91], s18 offen
	buffer_load_dword v79, v20, s[88:91], s15 offen
	buffer_load_dword v78, v20, s[88:91], s14 offen
	buffer_load_dword v77, v20, s[88:91], s13 offen
	buffer_load_dword v76, v20, s[88:91], s12 offen
	buffer_load_dword v75, v20, s[88:91], s11 offen
	buffer_load_dword v74, v20, s[88:91], s10 offen
	buffer_load_dword v73, v20, s[88:91], s9 offen
	buffer_load_dword v72, v20, s[88:91], s8 offen
	buffer_load_dword v71, v20, s[88:91], s7 offen
	buffer_load_dword v70, v20, s[88:91], s6 offen
	buffer_load_dword v69, v20, s[88:91], s5 offen
	buffer_load_dword v68, v20, s[88:91], s1 offen
	buffer_load_dword v67, v20, s[88:91], s3 offen
	buffer_load_dword v21, v20, s[88:91], s4 offen
	buffer_load_dword v29, v20, s[88:91], s2 offen
	buffer_load_dword v28, v20, s[88:91], s0 offen
	buffer_load_dword v65, v20, s[88:91], s39 offen
	buffer_load_dword v64, v20, s[88:91], s37 offen
	buffer_load_dword v63, v20, s[88:91], s41 offen
	buffer_load_dword v36, v20, s[88:91], s35 offen
	buffer_load_dword v34, v20, s[88:91], s42 offen
	buffer_load_dword v33, v20, s[88:91], s40 offen
	buffer_load_dword v31, v20, s[88:91], s38 offen
	buffer_load_dword v32, v20, s[88:91], s36 offen
	buffer_load_dword v62, v20, s[88:91], s43 offen
	buffer_load_dword v41, v20, s[88:91], s53 offen
	buffer_load_dword v40, v20, s[88:91], s52 offen
	buffer_load_dword v39, v20, s[88:91], s51 offen
	buffer_load_dword v38, v20, s[88:91], s50 offen
	buffer_load_dword v37, v20, s[88:91], s49 offen
	buffer_load_dword v26, v20, s[88:91], s48 offen
	buffer_load_dword v25, v20, s[88:91], s46 offen
	buffer_load_dword v61, v20, s[88:91], s97 offen
	buffer_load_dword v60, v20, s[88:91], s96 offen
	buffer_load_dword v59, v20, s[88:91], s71 offen
	buffer_load_dword v24, v20, s[88:91], s92 offen
	buffer_load_dword v23, v20, s[88:91], s95 offen
	buffer_load_dword v58, v20, s[88:91], s70 offen
	buffer_load_dword v57, v20, s[88:91], s69 offen
	buffer_load_dword v56, v20, s[88:91], s68 offen
	buffer_load_dword v55, v20, s[88:91], s67 offen
	buffer_load_dword v54, v20, s[88:91], s66 offen
	buffer_load_dword v53, v20, s[88:91], s65 offen
	buffer_load_dword v52, v20, s[88:91], s64 offen
	buffer_load_dword v51, v20, s[88:91], s63 offen
	buffer_load_dword v50, v20, s[88:91], s62 offen
	buffer_load_dword v49, v20, s[88:91], s61 offen
	buffer_load_dword v48, v20, s[88:91], s60 offen
	buffer_load_dword v47, v20, s[88:91], s59 offen
	buffer_load_dword v46, v20, s[88:91], s58 offen
	buffer_load_dword v45, v20, s[88:91], s57 offen
	buffer_load_dword v44, v20, s[88:91], s56 offen
	buffer_load_dword v43, v20, s[88:91], s55 offen
	buffer_load_dword v42, v20, s[88:91], s54 offen
	s_waitcnt vmcnt(0)
	s_mul_i32 s98, s93, s20
	s_add_i32 s99, s98, s20
	s_and_b64 vcc, exec, s[24:25]
	s_cbranch_vccz .Lscan_ssd
	v_lshl_add_u32 v188, s93, 8, v163
	ds_read_b64 v[166:167], v188
	ds_read_b64 v[168:169], v188 offset:256
	ds_read_b64 v[170:171], v188 offset:512
	ds_read_b64 v[172:173], v188 offset:768
	ds_read_b64 v[174:175], v188 offset:1024
	ds_read_b64 v[176:177], v188 offset:1280
	ds_read_b64 v[178:179], v188 offset:1536
	ds_read_b64 v[180:181], v188 offset:1792
	v_cvt_pk_bf16_f32 v182, v14, v15
	buffer_store_dword v182, v20, s[88:91], s98 offen
	v_lshlrev_b32_e32 v184, 16, v85
	v_and_b32_e32 v185, 0xffff0000, v85
	s_waitcnt lgkmcnt(7)
	v_pk_fma_f32 v[14:15], v[14:15], v[166:167], v[184:185]
	ds_read_b64 v[166:167], v188 offset:2048
	v_cvt_pk_bf16_f32 v183, v14, v15
	buffer_store_dword v183, v20, s[88:91], s99 offen
	v_lshlrev_b32_e32 v186, 16, v84
	v_and_b32_e32 v187, 0xffff0000, v84
	s_waitcnt lgkmcnt(7)
	v_pk_fma_f32 v[14:15], v[14:15], v[168:169], v[186:187]
	ds_read_b64 v[168:169], v188 offset:2304
	v_cvt_pk_bf16_f32 v182, v14, v15
	buffer_store_dword v182, v20, s[88:91], s19 offen
	v_lshlrev_b32_e32 v184, 16, v83
	v_and_b32_e32 v185, 0xffff0000, v83
	s_waitcnt lgkmcnt(7)
	v_pk_fma_f32 v[14:15], v[14:15], v[170:171], v[184:185]
	ds_read_b64 v[170:171], v188 offset:2560
	v_cvt_pk_bf16_f32 v183, v14, v15
	buffer_store_dword v183, v20, s[88:91], s18 offen
	v_lshlrev_b32_e32 v186, 16, v82
	v_and_b32_e32 v187, 0xffff0000, v82
	s_waitcnt lgkmcnt(7)
	v_pk_fma_f32 v[14:15], v[14:15], v[172:173], v[186:187]
	ds_read_b64 v[172:173], v188 offset:2816
	v_cvt_pk_bf16_f32 v182, v14, v15
	buffer_store_dword v182, v20, s[88:91], s17 offen
	v_lshlrev_b32_e32 v184, 16, v81
	v_and_b32_e32 v185, 0xffff0000, v81
	s_waitcnt lgkmcnt(7)
	v_pk_fma_f32 v[14:15], v[14:15], v[174:175], v[184:185]
	ds_read_b64 v[174:175], v188 offset:3072
	v_cvt_pk_bf16_f32 v183, v14, v15
	buffer_store_dword v183, v20, s[88:91], s16 offen
	v_lshlrev_b32_e32 v186, 16, v80
	v_and_b32_e32 v187, 0xffff0000, v80
	s_waitcnt lgkmcnt(7)
	v_pk_fma_f32 v[14:15], v[14:15], v[176:177], v[186:187]
	ds_read_b64 v[176:177], v188 offset:3328
	v_cvt_pk_bf16_f32 v182, v14, v15
	buffer_store_dword v182, v20, s[88:91], s15 offen
	v_lshlrev_b32_e32 v184, 16, v79
	v_and_b32_e32 v185, 0xffff0000, v79
	s_waitcnt lgkmcnt(7)
	v_pk_fma_f32 v[14:15], v[14:15], v[178:179], v[184:185]
	ds_read_b64 v[178:179], v188 offset:3584
	v_cvt_pk_bf16_f32 v183, v14, v15
	buffer_store_dword v183, v20, s[88:91], s14 offen
	v_lshlrev_b32_e32 v186, 16, v78
	v_and_b32_e32 v187, 0xffff0000, v78
	s_waitcnt lgkmcnt(7)
	v_pk_fma_f32 v[14:15], v[14:15], v[180:181], v[186:187]
	ds_read_b64 v[180:181], v188 offset:3840
	v_cvt_pk_bf16_f32 v182, v14, v15
	buffer_store_dword v182, v20, s[88:91], s13 offen
	v_lshlrev_b32_e32 v184, 16, v77
	v_and_b32_e32 v185, 0xffff0000, v77
	s_waitcnt lgkmcnt(7)
	v_pk_fma_f32 v[14:15], v[14:15], v[166:167], v[184:185]
	ds_read_b64 v[166:167], v188 offset:4096
	v_cvt_pk_bf16_f32 v183, v14, v15
	buffer_store_dword v183, v20, s[88:91], s12 offen
	v_lshlrev_b32_e32 v186, 16, v76
	v_and_b32_e32 v187, 0xffff0000, v76
	s_waitcnt lgkmcnt(7)
	v_pk_fma_f32 v[14:15], v[14:15], v[168:169], v[186:187]
	ds_read_b64 v[168:169], v188 offset:4352
	v_cvt_pk_bf16_f32 v182, v14, v15
	buffer_store_dword v182, v20, s[88:91], s11 offen
	v_lshlrev_b32_e32 v184, 16, v75
	v_and_b32_e32 v185, 0xffff0000, v75
	s_waitcnt lgkmcnt(7)
	v_pk_fma_f32 v[14:15], v[14:15], v[170:171], v[184:185]
	ds_read_b64 v[170:171], v188 offset:4608
	v_cvt_pk_bf16_f32 v183, v14, v15
	buffer_store_dword v183, v20, s[88:91], s10 offen
	v_lshlrev_b32_e32 v186, 16, v74
	v_and_b32_e32 v187, 0xffff0000, v74
	s_waitcnt lgkmcnt(7)
	v_pk_fma_f32 v[14:15], v[14:15], v[172:173], v[186:187]
	ds_read_b64 v[172:173], v188 offset:4864
	v_cvt_pk_bf16_f32 v182, v14, v15
	buffer_store_dword v182, v20, s[88:91], s9 offen
	v_lshlrev_b32_e32 v184, 16, v73
	v_and_b32_e32 v185, 0xffff0000, v73
	s_waitcnt lgkmcnt(7)
	v_pk_fma_f32 v[14:15], v[14:15], v[174:175], v[184:185]
	ds_read_b64 v[174:175], v188 offset:5120
	v_cvt_pk_bf16_f32 v183, v14, v15
	buffer_store_dword v183, v20, s[88:91], s8 offen
	v_lshlrev_b32_e32 v186, 16, v72
	v_and_b32_e32 v187, 0xffff0000, v72
	s_waitcnt lgkmcnt(7)
	v_pk_fma_f32 v[14:15], v[14:15], v[176:177], v[186:187]
	ds_read_b64 v[176:177], v188 offset:5376
	v_cvt_pk_bf16_f32 v182, v14, v15
	buffer_store_dword v182, v20, s[88:91], s7 offen
	v_lshlrev_b32_e32 v184, 16, v71
	v_and_b32_e32 v185, 0xffff0000, v71
	s_waitcnt lgkmcnt(7)
	v_pk_fma_f32 v[14:15], v[14:15], v[178:179], v[184:185]
	ds_read_b64 v[178:179], v188 offset:5632
	v_cvt_pk_bf16_f32 v183, v14, v15
	buffer_store_dword v183, v20, s[88:91], s6 offen
	v_lshlrev_b32_e32 v186, 16, v70
	v_and_b32_e32 v187, 0xffff0000, v70
	s_waitcnt lgkmcnt(7)
	v_pk_fma_f32 v[14:15], v[14:15], v[180:181], v[186:187]
	ds_read_b64 v[180:181], v188 offset:5888
	v_cvt_pk_bf16_f32 v182, v14, v15
	buffer_store_dword v182, v20, s[88:91], s5 offen
	v_lshlrev_b32_e32 v184, 16, v69
	v_and_b32_e32 v185, 0xffff0000, v69
	s_waitcnt lgkmcnt(7)
	v_pk_fma_f32 v[14:15], v[14:15], v[166:167], v[184:185]
	ds_read_b64 v[166:167], v188 offset:6144
	v_cvt_pk_bf16_f32 v183, v14, v15
	buffer_store_dword v183, v20, s[88:91], s1 offen
	v_lshlrev_b32_e32 v186, 16, v68
	v_and_b32_e32 v187, 0xffff0000, v68
	s_waitcnt lgkmcnt(7)
	v_pk_fma_f32 v[14:15], v[14:15], v[168:169], v[186:187]
	ds_read_b64 v[168:169], v188 offset:6400
	v_cvt_pk_bf16_f32 v182, v14, v15
	buffer_store_dword v182, v20, s[88:91], s3 offen
	v_lshlrev_b32_e32 v184, 16, v67
	v_and_b32_e32 v185, 0xffff0000, v67
	s_waitcnt lgkmcnt(7)
	v_pk_fma_f32 v[14:15], v[14:15], v[170:171], v[184:185]
	ds_read_b64 v[170:171], v188 offset:6656
	v_cvt_pk_bf16_f32 v183, v14, v15
	buffer_store_dword v183, v20, s[88:91], s23 offen
	v_lshlrev_b32_e32 v186, 16, v66
	v_and_b32_e32 v187, 0xffff0000, v66
	s_waitcnt lgkmcnt(7)
	v_pk_fma_f32 v[14:15], v[14:15], v[172:173], v[186:187]
	ds_read_b64 v[172:173], v188 offset:6912
	v_cvt_pk_bf16_f32 v182, v14, v15
	buffer_store_dword v182, v20, s[88:91], s39 offen
	v_lshlrev_b32_e32 v184, 16, v65
	v_and_b32_e32 v185, 0xffff0000, v65
	s_waitcnt lgkmcnt(7)
	v_pk_fma_f32 v[14:15], v[14:15], v[174:175], v[184:185]
	ds_read_b64 v[174:175], v188 offset:7168
	v_cvt_pk_bf16_f32 v183, v14, v15
	buffer_store_dword v183, v20, s[88:91], s37 offen
	v_lshlrev_b32_e32 v186, 16, v64
	v_and_b32_e32 v187, 0xffff0000, v64
	s_waitcnt lgkmcnt(7)
	v_pk_fma_f32 v[14:15], v[14:15], v[176:177], v[186:187]
	ds_read_b64 v[176:177], v188 offset:7424
	v_cvt_pk_bf16_f32 v182, v14, v15
	buffer_store_dword v182, v20, s[88:91], s41 offen
	v_lshlrev_b32_e32 v184, 16, v63
	v_and_b32_e32 v185, 0xffff0000, v63
	s_waitcnt lgkmcnt(7)
	v_pk_fma_f32 v[14:15], v[14:15], v[178:179], v[184:185]
	ds_read_b64 v[178:179], v188 offset:7680
	v_cvt_pk_bf16_f32 v183, v14, v15
	buffer_store_dword v183, v20, s[88:91], s43 offen
	v_lshlrev_b32_e32 v186, 16, v62
	v_and_b32_e32 v187, 0xffff0000, v62
	s_waitcnt lgkmcnt(7)
	v_pk_fma_f32 v[14:15], v[14:15], v[180:181], v[186:187]
	ds_read_b64 v[180:181], v188 offset:7936
	v_cvt_pk_bf16_f32 v182, v14, v15
	buffer_store_dword v182, v20, s[88:91], s97 offen
	v_lshlrev_b32_e32 v184, 16, v61
	v_and_b32_e32 v185, 0xffff0000, v61
	s_waitcnt lgkmcnt(7)
	v_pk_fma_f32 v[14:15], v[14:15], v[166:167], v[184:185]
	ds_read_b64 v[166:167], v188 offset:8192
	v_cvt_pk_bf16_f32 v183, v14, v15
	buffer_store_dword v183, v20, s[88:91], s96 offen
	v_lshlrev_b32_e32 v186, 16, v60
	v_and_b32_e32 v187, 0xffff0000, v60
	s_waitcnt lgkmcnt(7)
	v_pk_fma_f32 v[14:15], v[14:15], v[168:169], v[186:187]
	ds_read_b64 v[168:169], v188 offset:8448
	v_cvt_pk_bf16_f32 v182, v14, v15
	buffer_store_dword v182, v20, s[88:91], s71 offen
	v_lshlrev_b32_e32 v184, 16, v59
	v_and_b32_e32 v185, 0xffff0000, v59
	s_waitcnt lgkmcnt(7)
	v_pk_fma_f32 v[14:15], v[14:15], v[170:171], v[184:185]
	ds_read_b64 v[170:171], v188 offset:8704
	v_cvt_pk_bf16_f32 v183, v14, v15
	buffer_store_dword v183, v20, s[88:91], s70 offen
	v_lshlrev_b32_e32 v186, 16, v58
	v_and_b32_e32 v187, 0xffff0000, v58
	s_waitcnt lgkmcnt(7)
	v_pk_fma_f32 v[14:15], v[14:15], v[172:173], v[186:187]
	ds_read_b64 v[172:173], v188 offset:8960
	v_cvt_pk_bf16_f32 v182, v14, v15
	buffer_store_dword v182, v20, s[88:91], s69 offen
	v_lshlrev_b32_e32 v184, 16, v57
	v_and_b32_e32 v185, 0xffff0000, v57
	s_waitcnt lgkmcnt(7)
	v_pk_fma_f32 v[14:15], v[14:15], v[174:175], v[184:185]
	ds_read_b64 v[174:175], v188 offset:9216
	v_cvt_pk_bf16_f32 v183, v14, v15
	buffer_store_dword v183, v20, s[88:91], s68 offen
	v_lshlrev_b32_e32 v186, 16, v56
	v_and_b32_e32 v187, 0xffff0000, v56
	s_waitcnt lgkmcnt(7)
	v_pk_fma_f32 v[14:15], v[14:15], v[176:177], v[186:187]
	ds_read_b64 v[176:177], v188 offset:9472
	v_cvt_pk_bf16_f32 v182, v14, v15
	buffer_store_dword v182, v20, s[88:91], s67 offen
	v_lshlrev_b32_e32 v184, 16, v55
	v_and_b32_e32 v185, 0xffff0000, v55
	s_waitcnt lgkmcnt(7)
	v_pk_fma_f32 v[14:15], v[14:15], v[178:179], v[184:185]
	ds_read_b64 v[178:179], v188 offset:9728
	v_cvt_pk_bf16_f32 v183, v14, v15
	buffer_store_dword v183, v20, s[88:91], s66 offen
	v_lshlrev_b32_e32 v186, 16, v54
	v_and_b32_e32 v187, 0xffff0000, v54
	s_waitcnt lgkmcnt(7)
	v_pk_fma_f32 v[14:15], v[14:15], v[180:181], v[186:187]
	ds_read_b64 v[180:181], v188 offset:9984
	v_cvt_pk_bf16_f32 v182, v14, v15
	buffer_store_dword v182, v20, s[88:91], s65 offen
	v_lshlrev_b32_e32 v184, 16, v53
	v_and_b32_e32 v185, 0xffff0000, v53
	s_waitcnt lgkmcnt(7)
	v_pk_fma_f32 v[14:15], v[14:15], v[166:167], v[184:185]
	ds_read_b64 v[166:167], v188 offset:10240
	v_cvt_pk_bf16_f32 v183, v14, v15
	buffer_store_dword v183, v20, s[88:91], s64 offen
	v_lshlrev_b32_e32 v186, 16, v52
	v_and_b32_e32 v187, 0xffff0000, v52
	s_waitcnt lgkmcnt(7)
	v_pk_fma_f32 v[14:15], v[14:15], v[168:169], v[186:187]
	ds_read_b64 v[168:169], v188 offset:10496
	v_cvt_pk_bf16_f32 v182, v14, v15
	buffer_store_dword v182, v20, s[88:91], s63 offen
	v_lshlrev_b32_e32 v184, 16, v51
	v_and_b32_e32 v185, 0xffff0000, v51
	s_waitcnt lgkmcnt(7)
	v_pk_fma_f32 v[14:15], v[14:15], v[170:171], v[184:185]
	ds_read_b64 v[170:171], v188 offset:10752
	v_cvt_pk_bf16_f32 v183, v14, v15
	buffer_store_dword v183, v20, s[88:91], s62 offen
	v_lshlrev_b32_e32 v186, 16, v50
	v_and_b32_e32 v187, 0xffff0000, v50
	s_waitcnt lgkmcnt(7)
	v_pk_fma_f32 v[14:15], v[14:15], v[172:173], v[186:187]
	ds_read_b64 v[172:173], v188 offset:11008
	v_cvt_pk_bf16_f32 v182, v14, v15
	buffer_store_dword v182, v20, s[88:91], s61 offen
	v_lshlrev_b32_e32 v184, 16, v49
	v_and_b32_e32 v185, 0xffff0000, v49
	s_waitcnt lgkmcnt(7)
	v_pk_fma_f32 v[14:15], v[14:15], v[174:175], v[184:185]
	ds_read_b64 v[174:175], v188 offset:11264
	v_cvt_pk_bf16_f32 v183, v14, v15
	buffer_store_dword v183, v20, s[88:91], s60 offen
	v_lshlrev_b32_e32 v186, 16, v48
	v_and_b32_e32 v187, 0xffff0000, v48
	s_waitcnt lgkmcnt(7)
	v_pk_fma_f32 v[14:15], v[14:15], v[176:177], v[186:187]
	ds_read_b64 v[176:177], v188 offset:11520
	v_cvt_pk_bf16_f32 v182, v14, v15
	buffer_store_dword v182, v20, s[88:91], s59 offen
	v_lshlrev_b32_e32 v184, 16, v47
	v_and_b32_e32 v185, 0xffff0000, v47
	s_waitcnt lgkmcnt(7)
	v_pk_fma_f32 v[14:15], v[14:15], v[178:179], v[184:185]
	ds_read_b64 v[178:179], v188 offset:11776
	v_cvt_pk_bf16_f32 v183, v14, v15
	buffer_store_dword v183, v20, s[88:91], s58 offen
	v_lshlrev_b32_e32 v186, 16, v46
	v_and_b32_e32 v187, 0xffff0000, v46
	s_waitcnt lgkmcnt(7)
	v_pk_fma_f32 v[14:15], v[14:15], v[180:181], v[186:187]
	ds_read_b64 v[180:181], v188 offset:12032
	v_cvt_pk_bf16_f32 v182, v14, v15
	buffer_store_dword v182, v20, s[88:91], s57 offen
	v_lshlrev_b32_e32 v184, 16, v45
	v_and_b32_e32 v185, 0xffff0000, v45
	s_waitcnt lgkmcnt(7)
	v_pk_fma_f32 v[14:15], v[14:15], v[166:167], v[184:185]
	ds_read_b64 v[166:167], v188 offset:12288
	v_cvt_pk_bf16_f32 v183, v14, v15
	buffer_store_dword v183, v20, s[88:91], s56 offen
	v_lshlrev_b32_e32 v186, 16, v44
	v_and_b32_e32 v187, 0xffff0000, v44
	s_waitcnt lgkmcnt(7)
	v_pk_fma_f32 v[14:15], v[14:15], v[168:169], v[186:187]
	ds_read_b64 v[168:169], v188 offset:12544
	v_cvt_pk_bf16_f32 v182, v14, v15
	buffer_store_dword v182, v20, s[88:91], s55 offen
	v_lshlrev_b32_e32 v184, 16, v43
	v_and_b32_e32 v185, 0xffff0000, v43
	s_waitcnt lgkmcnt(7)
	v_pk_fma_f32 v[14:15], v[14:15], v[170:171], v[184:185]
	ds_read_b64 v[170:171], v188 offset:12800
	v_cvt_pk_bf16_f32 v183, v14, v15
	buffer_store_dword v183, v20, s[88:91], s54 offen
	v_lshlrev_b32_e32 v186, 16, v42
	v_and_b32_e32 v187, 0xffff0000, v42
	s_waitcnt lgkmcnt(7)
	v_pk_fma_f32 v[14:15], v[14:15], v[172:173], v[186:187]
	ds_read_b64 v[172:173], v188 offset:13056
	v_cvt_pk_bf16_f32 v182, v14, v15
	buffer_store_dword v182, v20, s[88:91], s53 offen
	v_lshlrev_b32_e32 v184, 16, v41
	v_and_b32_e32 v185, 0xffff0000, v41
	s_waitcnt lgkmcnt(7)
	v_pk_fma_f32 v[14:15], v[14:15], v[174:175], v[184:185]
	ds_read_b64 v[174:175], v188 offset:13312
	v_cvt_pk_bf16_f32 v183, v14, v15
	buffer_store_dword v183, v20, s[88:91], s52 offen
	v_lshlrev_b32_e32 v186, 16, v40
	v_and_b32_e32 v187, 0xffff0000, v40
	s_waitcnt lgkmcnt(7)
	v_pk_fma_f32 v[14:15], v[14:15], v[176:177], v[186:187]
	ds_read_b64 v[176:177], v188 offset:13568
	v_cvt_pk_bf16_f32 v182, v14, v15
	buffer_store_dword v182, v20, s[88:91], s51 offen
	v_lshlrev_b32_e32 v184, 16, v39
	v_and_b32_e32 v185, 0xffff0000, v39
	s_waitcnt lgkmcnt(7)
	v_pk_fma_f32 v[14:15], v[14:15], v[178:179], v[184:185]
	ds_read_b64 v[178:179], v188 offset:13824
	v_cvt_pk_bf16_f32 v183, v14, v15
	buffer_store_dword v183, v20, s[88:91], s50 offen
	v_lshlrev_b32_e32 v186, 16, v38
	v_and_b32_e32 v187, 0xffff0000, v38
	s_waitcnt lgkmcnt(7)
	v_pk_fma_f32 v[14:15], v[14:15], v[180:181], v[186:187]
	ds_read_b64 v[180:181], v188 offset:14080
	v_cvt_pk_bf16_f32 v182, v14, v15
	buffer_store_dword v182, v20, s[88:91], s49 offen
	v_lshlrev_b32_e32 v184, 16, v37
	v_and_b32_e32 v185, 0xffff0000, v37
	s_waitcnt lgkmcnt(7)
	v_pk_fma_f32 v[14:15], v[14:15], v[166:167], v[184:185]
	ds_read_b64 v[166:167], v188 offset:14336
	v_cvt_pk_bf16_f32 v183, v14, v15
	buffer_store_dword v183, v20, s[88:91], s35 offen
	v_lshlrev_b32_e32 v186, 16, v36
	v_and_b32_e32 v187, 0xffff0000, v36
	s_waitcnt lgkmcnt(7)
	v_pk_fma_f32 v[14:15], v[14:15], v[168:169], v[186:187]
	ds_read_b64 v[168:169], v188 offset:14592
	v_cvt_pk_bf16_f32 v182, v14, v15
	buffer_store_dword v182, v20, s[88:91], s34 offen
	v_lshlrev_b32_e32 v184, 16, v35
	v_and_b32_e32 v185, 0xffff0000, v35
	s_waitcnt lgkmcnt(7)
	v_pk_fma_f32 v[14:15], v[14:15], v[170:171], v[184:185]
	ds_read_b64 v[170:171], v188 offset:14848
	v_cvt_pk_bf16_f32 v183, v14, v15
	buffer_store_dword v183, v20, s[88:91], s42 offen
	v_lshlrev_b32_e32 v186, 16, v34
	v_and_b32_e32 v187, 0xffff0000, v34
	s_waitcnt lgkmcnt(7)
	v_pk_fma_f32 v[14:15], v[14:15], v[172:173], v[186:187]
	ds_read_b64 v[172:173], v188 offset:15104
	v_cvt_pk_bf16_f32 v182, v14, v15
	buffer_store_dword v182, v20, s[88:91], s40 offen
	v_lshlrev_b32_e32 v184, 16, v33
	v_and_b32_e32 v185, 0xffff0000, v33
	s_waitcnt lgkmcnt(7)
	v_pk_fma_f32 v[14:15], v[14:15], v[174:175], v[184:185]
	ds_read_b64 v[174:175], v188 offset:15360
	v_cvt_pk_bf16_f32 v183, v14, v15
	buffer_store_dword v183, v20, s[88:91], s36 offen
	v_lshlrev_b32_e32 v186, 16, v32
	v_and_b32_e32 v187, 0xffff0000, v32
	s_waitcnt lgkmcnt(7)
	v_pk_fma_f32 v[14:15], v[14:15], v[176:177], v[186:187]
	ds_read_b64 v[176:177], v188 offset:15616
	v_cvt_pk_bf16_f32 v182, v14, v15
	buffer_store_dword v182, v20, s[88:91], s38 offen
	v_lshlrev_b32_e32 v184, 16, v31
	v_and_b32_e32 v185, 0xffff0000, v31
	s_waitcnt lgkmcnt(7)
	v_pk_fma_f32 v[14:15], v[14:15], v[178:179], v[184:185]
	ds_read_b64 v[178:179], v188 offset:15872
	v_cvt_pk_bf16_f32 v183, v14, v15
	buffer_store_dword v183, v20, s[88:91], s22 offen
	v_lshlrev_b32_e32 v186, 16, v30
	v_and_b32_e32 v187, 0xffff0000, v30
	s_waitcnt lgkmcnt(7)
	v_pk_fma_f32 v[14:15], v[14:15], v[180:181], v[186:187]
	ds_read_b64 v[180:181], v188 offset:16128
	v_cvt_pk_bf16_f32 v182, v14, v15
	buffer_store_dword v182, v20, s[88:91], s2 offen
	v_lshlrev_b32_e32 v184, 16, v29
	v_and_b32_e32 v185, 0xffff0000, v29
	s_waitcnt lgkmcnt(7)
	v_pk_fma_f32 v[14:15], v[14:15], v[166:167], v[184:185]
	s_nop 0
	v_cvt_pk_bf16_f32 v183, v14, v15
	buffer_store_dword v183, v20, s[88:91], s0 offen
	v_lshlrev_b32_e32 v186, 16, v28
	v_and_b32_e32 v187, 0xffff0000, v28
	s_waitcnt lgkmcnt(6)
	v_pk_fma_f32 v[14:15], v[14:15], v[168:169], v[186:187]
	s_nop 0
	v_cvt_pk_bf16_f32 v182, v14, v15
	buffer_store_dword v182, v20, s[88:91], s48 offen
	v_lshlrev_b32_e32 v184, 16, v26
	v_and_b32_e32 v185, 0xffff0000, v26
	s_waitcnt lgkmcnt(5)
	v_pk_fma_f32 v[14:15], v[14:15], v[170:171], v[184:185]
	s_nop 0
	v_cvt_pk_bf16_f32 v183, v14, v15
	buffer_store_dword v183, v20, s[88:91], s46 offen
	v_lshlrev_b32_e32 v186, 16, v25
	v_and_b32_e32 v187, 0xffff0000, v25
	s_waitcnt lgkmcnt(4)
	v_pk_fma_f32 v[14:15], v[14:15], v[172:173], v[186:187]
	s_nop 0
	v_cvt_pk_bf16_f32 v182, v14, v15
	buffer_store_dword v182, v20, s[88:91], s92 offen
	v_lshlrev_b32_e32 v184, 16, v24
	v_and_b32_e32 v185, 0xffff0000, v24
	s_waitcnt lgkmcnt(3)
	v_pk_fma_f32 v[14:15], v[14:15], v[174:175], v[184:185]
	s_nop 0
	v_cvt_pk_bf16_f32 v183, v14, v15
	buffer_store_dword v183, v20, s[88:91], s95 offen
	v_lshlrev_b32_e32 v186, 16, v23
	v_and_b32_e32 v187, 0xffff0000, v23
	s_waitcnt lgkmcnt(2)
	v_pk_fma_f32 v[14:15], v[14:15], v[176:177], v[186:187]
	s_nop 0
	v_cvt_pk_bf16_f32 v182, v14, v15
	buffer_store_dword v182, v20, s[88:91], s4 offen
	v_lshlrev_b32_e32 v184, 16, v21
	v_and_b32_e32 v185, 0xffff0000, v21
	s_waitcnt lgkmcnt(1)
	v_pk_fma_f32 v[14:15], v[14:15], v[178:179], v[184:185]
	s_nop 0
	v_cvt_pk_bf16_f32 v183, v14, v15
	buffer_store_dword v183, v20, s[88:91], s26 offen
	v_lshlrev_b32_e32 v186, 16, v22
	v_and_b32_e32 v187, 0xffff0000, v22
	s_waitcnt lgkmcnt(0)
	v_pk_fma_f32 v[14:15], v[14:15], v[180:181], v[186:187]
	s_branch .Lscan_done
.Lscan_ssd:
	v_mov_b32_e32 v188, s93
	v_lshlrev_b32_e32 v188, 2, v188
	ds_read_b32 v166, v188
	ds_read_b32 v168, v188 offset:4
	ds_read_b32 v170, v188 offset:8
	ds_read_b32 v172, v188 offset:12
	ds_read_b32 v174, v188 offset:16
	ds_read_b32 v176, v188 offset:20
	ds_read_b32 v178, v188 offset:24
	ds_read_b32 v180, v188 offset:28
	v_cvt_pk_bf16_f32 v182, v14, v15
	buffer_store_dword v182, v20, s[88:91], s98 offen
	v_lshlrev_b32_e32 v184, 16, v85
	v_and_b32_e32 v185, 0xffff0000, v85
	s_waitcnt lgkmcnt(7)
	v_pk_fma_f32 v[14:15], v[14:15], v[166:167], v[184:185] op_sel_hi:[1,0,1]
	ds_read_b32 v166, v188 offset:32
	v_cvt_pk_bf16_f32 v183, v14, v15
	buffer_store_dword v183, v20, s[88:91], s99 offen
	v_lshlrev_b32_e32 v186, 16, v84
	v_and_b32_e32 v187, 0xffff0000, v84
	s_waitcnt lgkmcnt(7)
	v_pk_fma_f32 v[14:15], v[14:15], v[168:169], v[186:187] op_sel_hi:[1,0,1]
	ds_read_b32 v168, v188 offset:36
	v_cvt_pk_bf16_f32 v182, v14, v15
	buffer_store_dword v182, v20, s[88:91], s19 offen
	v_lshlrev_b32_e32 v184, 16, v83
	v_and_b32_e32 v185, 0xffff0000, v83
	s_waitcnt lgkmcnt(7)
	v_pk_fma_f32 v[14:15], v[14:15], v[170:171], v[184:185] op_sel_hi:[1,0,1]
	ds_read_b32 v170, v188 offset:40
	v_cvt_pk_bf16_f32 v183, v14, v15
	buffer_store_dword v183, v20, s[88:91], s18 offen
	v_lshlrev_b32_e32 v186, 16, v82
	v_and_b32_e32 v187, 0xffff0000, v82
	s_waitcnt lgkmcnt(7)
	v_pk_fma_f32 v[14:15], v[14:15], v[172:173], v[186:187] op_sel_hi:[1,0,1]
	ds_read_b32 v172, v188 offset:44
	v_cvt_pk_bf16_f32 v182, v14, v15
	buffer_store_dword v182, v20, s[88:91], s17 offen
	v_lshlrev_b32_e32 v184, 16, v81
	v_and_b32_e32 v185, 0xffff0000, v81
	s_waitcnt lgkmcnt(7)
	v_pk_fma_f32 v[14:15], v[14:15], v[174:175], v[184:185] op_sel_hi:[1,0,1]
	ds_read_b32 v174, v188 offset:48
	v_cvt_pk_bf16_f32 v183, v14, v15
	buffer_store_dword v183, v20, s[88:91], s16 offen
	v_lshlrev_b32_e32 v186, 16, v80
	v_and_b32_e32 v187, 0xffff0000, v80
	s_waitcnt lgkmcnt(7)
	v_pk_fma_f32 v[14:15], v[14:15], v[176:177], v[186:187] op_sel_hi:[1,0,1]
	ds_read_b32 v176, v188 offset:52
	v_cvt_pk_bf16_f32 v182, v14, v15
	buffer_store_dword v182, v20, s[88:91], s15 offen
	v_lshlrev_b32_e32 v184, 16, v79
	v_and_b32_e32 v185, 0xffff0000, v79
	s_waitcnt lgkmcnt(7)
	v_pk_fma_f32 v[14:15], v[14:15], v[178:179], v[184:185] op_sel_hi:[1,0,1]
	ds_read_b32 v178, v188 offset:56
	v_cvt_pk_bf16_f32 v183, v14, v15
	buffer_store_dword v183, v20, s[88:91], s14 offen
	v_lshlrev_b32_e32 v186, 16, v78
	v_and_b32_e32 v187, 0xffff0000, v78
	s_waitcnt lgkmcnt(7)
	v_pk_fma_f32 v[14:15], v[14:15], v[180:181], v[186:187] op_sel_hi:[1,0,1]
	ds_read_b32 v180, v188 offset:60
	v_cvt_pk_bf16_f32 v182, v14, v15
	buffer_store_dword v182, v20, s[88:91], s13 offen
	v_lshlrev_b32_e32 v184, 16, v77
	v_and_b32_e32 v185, 0xffff0000, v77
	s_waitcnt lgkmcnt(7)
	v_pk_fma_f32 v[14:15], v[14:15], v[166:167], v[184:185] op_sel_hi:[1,0,1]
	ds_read_b32 v166, v188 offset:64
	v_cvt_pk_bf16_f32 v183, v14, v15
	buffer_store_dword v183, v20, s[88:91], s12 offen
	v_lshlrev_b32_e32 v186, 16, v76
	v_and_b32_e32 v187, 0xffff0000, v76
	s_waitcnt lgkmcnt(7)
	v_pk_fma_f32 v[14:15], v[14:15], v[168:169], v[186:187] op_sel_hi:[1,0,1]
	ds_read_b32 v168, v188 offset:68
	v_cvt_pk_bf16_f32 v182, v14, v15
	buffer_store_dword v182, v20, s[88:91], s11 offen
	v_lshlrev_b32_e32 v184, 16, v75
	v_and_b32_e32 v185, 0xffff0000, v75
	s_waitcnt lgkmcnt(7)
	v_pk_fma_f32 v[14:15], v[14:15], v[170:171], v[184:185] op_sel_hi:[1,0,1]
	ds_read_b32 v170, v188 offset:72
	v_cvt_pk_bf16_f32 v183, v14, v15
	buffer_store_dword v183, v20, s[88:91], s10 offen
	v_lshlrev_b32_e32 v186, 16, v74
	v_and_b32_e32 v187, 0xffff0000, v74
	s_waitcnt lgkmcnt(7)
	v_pk_fma_f32 v[14:15], v[14:15], v[172:173], v[186:187] op_sel_hi:[1,0,1]
	ds_read_b32 v172, v188 offset:76
	v_cvt_pk_bf16_f32 v182, v14, v15
	buffer_store_dword v182, v20, s[88:91], s9 offen
	v_lshlrev_b32_e32 v184, 16, v73
	v_and_b32_e32 v185, 0xffff0000, v73
	s_waitcnt lgkmcnt(7)
	v_pk_fma_f32 v[14:15], v[14:15], v[174:175], v[184:185] op_sel_hi:[1,0,1]
	ds_read_b32 v174, v188 offset:80
	v_cvt_pk_bf16_f32 v183, v14, v15
	buffer_store_dword v183, v20, s[88:91], s8 offen
	v_lshlrev_b32_e32 v186, 16, v72
	v_and_b32_e32 v187, 0xffff0000, v72
	s_waitcnt lgkmcnt(7)
	v_pk_fma_f32 v[14:15], v[14:15], v[176:177], v[186:187] op_sel_hi:[1,0,1]
	ds_read_b32 v176, v188 offset:84
	v_cvt_pk_bf16_f32 v182, v14, v15
	buffer_store_dword v182, v20, s[88:91], s7 offen
	v_lshlrev_b32_e32 v184, 16, v71
	v_and_b32_e32 v185, 0xffff0000, v71
	s_waitcnt lgkmcnt(7)
	v_pk_fma_f32 v[14:15], v[14:15], v[178:179], v[184:185] op_sel_hi:[1,0,1]
	ds_read_b32 v178, v188 offset:88
	v_cvt_pk_bf16_f32 v183, v14, v15
	buffer_store_dword v183, v20, s[88:91], s6 offen
	v_lshlrev_b32_e32 v186, 16, v70
	v_and_b32_e32 v187, 0xffff0000, v70
	s_waitcnt lgkmcnt(7)
	v_pk_fma_f32 v[14:15], v[14:15], v[180:181], v[186:187] op_sel_hi:[1,0,1]
	ds_read_b32 v180, v188 offset:92
	v_cvt_pk_bf16_f32 v182, v14, v15
	buffer_store_dword v182, v20, s[88:91], s5 offen
	v_lshlrev_b32_e32 v184, 16, v69
	v_and_b32_e32 v185, 0xffff0000, v69
	s_waitcnt lgkmcnt(7)
	v_pk_fma_f32 v[14:15], v[14:15], v[166:167], v[184:185] op_sel_hi:[1,0,1]
	ds_read_b32 v166, v188 offset:96
	v_cvt_pk_bf16_f32 v183, v14, v15
	buffer_store_dword v183, v20, s[88:91], s1 offen
	v_lshlrev_b32_e32 v186, 16, v68
	v_and_b32_e32 v187, 0xffff0000, v68
	s_waitcnt lgkmcnt(7)
	v_pk_fma_f32 v[14:15], v[14:15], v[168:169], v[186:187] op_sel_hi:[1,0,1]
	ds_read_b32 v168, v188 offset:100
	v_cvt_pk_bf16_f32 v182, v14, v15
	buffer_store_dword v182, v20, s[88:91], s3 offen
	v_lshlrev_b32_e32 v184, 16, v67
	v_and_b32_e32 v185, 0xffff0000, v67
	s_waitcnt lgkmcnt(7)
	v_pk_fma_f32 v[14:15], v[14:15], v[170:171], v[184:185] op_sel_hi:[1,0,1]
	ds_read_b32 v170, v188 offset:104
	v_cvt_pk_bf16_f32 v183, v14, v15
	buffer_store_dword v183, v20, s[88:91], s23 offen
	v_lshlrev_b32_e32 v186, 16, v66
	v_and_b32_e32 v187, 0xffff0000, v66
	s_waitcnt lgkmcnt(7)
	v_pk_fma_f32 v[14:15], v[14:15], v[172:173], v[186:187] op_sel_hi:[1,0,1]
	ds_read_b32 v172, v188 offset:108
	v_cvt_pk_bf16_f32 v182, v14, v15
	buffer_store_dword v182, v20, s[88:91], s39 offen
	v_lshlrev_b32_e32 v184, 16, v65
	v_and_b32_e32 v185, 0xffff0000, v65
	s_waitcnt lgkmcnt(7)
	v_pk_fma_f32 v[14:15], v[14:15], v[174:175], v[184:185] op_sel_hi:[1,0,1]
	ds_read_b32 v174, v188 offset:112
	v_cvt_pk_bf16_f32 v183, v14, v15
	buffer_store_dword v183, v20, s[88:91], s37 offen
	v_lshlrev_b32_e32 v186, 16, v64
	v_and_b32_e32 v187, 0xffff0000, v64
	s_waitcnt lgkmcnt(7)
	v_pk_fma_f32 v[14:15], v[14:15], v[176:177], v[186:187] op_sel_hi:[1,0,1]
	ds_read_b32 v176, v188 offset:116
	v_cvt_pk_bf16_f32 v182, v14, v15
	buffer_store_dword v182, v20, s[88:91], s41 offen
	v_lshlrev_b32_e32 v184, 16, v63
	v_and_b32_e32 v185, 0xffff0000, v63
	s_waitcnt lgkmcnt(7)
	v_pk_fma_f32 v[14:15], v[14:15], v[178:179], v[184:185] op_sel_hi:[1,0,1]
	ds_read_b32 v178, v188 offset:120
	v_cvt_pk_bf16_f32 v183, v14, v15
	buffer_store_dword v183, v20, s[88:91], s43 offen
	v_lshlrev_b32_e32 v186, 16, v62
	v_and_b32_e32 v187, 0xffff0000, v62
	s_waitcnt lgkmcnt(7)
	v_pk_fma_f32 v[14:15], v[14:15], v[180:181], v[186:187] op_sel_hi:[1,0,1]
	ds_read_b32 v180, v188 offset:124
	v_cvt_pk_bf16_f32 v182, v14, v15
	buffer_store_dword v182, v20, s[88:91], s97 offen
	v_lshlrev_b32_e32 v184, 16, v61
	v_and_b32_e32 v185, 0xffff0000, v61
	s_waitcnt lgkmcnt(7)
	v_pk_fma_f32 v[14:15], v[14:15], v[166:167], v[184:185] op_sel_hi:[1,0,1]
	ds_read_b32 v166, v188 offset:128
	v_cvt_pk_bf16_f32 v183, v14, v15
	buffer_store_dword v183, v20, s[88:91], s96 offen
	v_lshlrev_b32_e32 v186, 16, v60
	v_and_b32_e32 v187, 0xffff0000, v60
	s_waitcnt lgkmcnt(7)
	v_pk_fma_f32 v[14:15], v[14:15], v[168:169], v[186:187] op_sel_hi:[1,0,1]
	ds_read_b32 v168, v188 offset:132
	v_cvt_pk_bf16_f32 v182, v14, v15
	buffer_store_dword v182, v20, s[88:91], s71 offen
	v_lshlrev_b32_e32 v184, 16, v59
	v_and_b32_e32 v185, 0xffff0000, v59
	s_waitcnt lgkmcnt(7)
	v_pk_fma_f32 v[14:15], v[14:15], v[170:171], v[184:185] op_sel_hi:[1,0,1]
	ds_read_b32 v170, v188 offset:136
	v_cvt_pk_bf16_f32 v183, v14, v15
	buffer_store_dword v183, v20, s[88:91], s70 offen
	v_lshlrev_b32_e32 v186, 16, v58
	v_and_b32_e32 v187, 0xffff0000, v58
	s_waitcnt lgkmcnt(7)
	v_pk_fma_f32 v[14:15], v[14:15], v[172:173], v[186:187] op_sel_hi:[1,0,1]
	ds_read_b32 v172, v188 offset:140
	v_cvt_pk_bf16_f32 v182, v14, v15
	buffer_store_dword v182, v20, s[88:91], s69 offen
	v_lshlrev_b32_e32 v184, 16, v57
	v_and_b32_e32 v185, 0xffff0000, v57
	s_waitcnt lgkmcnt(7)
	v_pk_fma_f32 v[14:15], v[14:15], v[174:175], v[184:185] op_sel_hi:[1,0,1]
	ds_read_b32 v174, v188 offset:144
	v_cvt_pk_bf16_f32 v183, v14, v15
	buffer_store_dword v183, v20, s[88:91], s68 offen
	v_lshlrev_b32_e32 v186, 16, v56
	v_and_b32_e32 v187, 0xffff0000, v56
	s_waitcnt lgkmcnt(7)
	v_pk_fma_f32 v[14:15], v[14:15], v[176:177], v[186:187] op_sel_hi:[1,0,1]
	ds_read_b32 v176, v188 offset:148
	v_cvt_pk_bf16_f32 v182, v14, v15
	buffer_store_dword v182, v20, s[88:91], s67 offen
	v_lshlrev_b32_e32 v184, 16, v55
	v_and_b32_e32 v185, 0xffff0000, v55
	s_waitcnt lgkmcnt(7)
	v_pk_fma_f32 v[14:15], v[14:15], v[178:179], v[184:185] op_sel_hi:[1,0,1]
	ds_read_b32 v178, v188 offset:152
	v_cvt_pk_bf16_f32 v183, v14, v15
	buffer_store_dword v183, v20, s[88:91], s66 offen
	v_lshlrev_b32_e32 v186, 16, v54
	v_and_b32_e32 v187, 0xffff0000, v54
	s_waitcnt lgkmcnt(7)
	v_pk_fma_f32 v[14:15], v[14:15], v[180:181], v[186:187] op_sel_hi:[1,0,1]
	ds_read_b32 v180, v188 offset:156
	v_cvt_pk_bf16_f32 v182, v14, v15
	buffer_store_dword v182, v20, s[88:91], s65 offen
	v_lshlrev_b32_e32 v184, 16, v53
	v_and_b32_e32 v185, 0xffff0000, v53
	s_waitcnt lgkmcnt(7)
	v_pk_fma_f32 v[14:15], v[14:15], v[166:167], v[184:185] op_sel_hi:[1,0,1]
	ds_read_b32 v166, v188 offset:160
	v_cvt_pk_bf16_f32 v183, v14, v15
	buffer_store_dword v183, v20, s[88:91], s64 offen
	v_lshlrev_b32_e32 v186, 16, v52
	v_and_b32_e32 v187, 0xffff0000, v52
	s_waitcnt lgkmcnt(7)
	v_pk_fma_f32 v[14:15], v[14:15], v[168:169], v[186:187] op_sel_hi:[1,0,1]
	ds_read_b32 v168, v188 offset:164
	v_cvt_pk_bf16_f32 v182, v14, v15
	buffer_store_dword v182, v20, s[88:91], s63 offen
	v_lshlrev_b32_e32 v184, 16, v51
	v_and_b32_e32 v185, 0xffff0000, v51
	s_waitcnt lgkmcnt(7)
	v_pk_fma_f32 v[14:15], v[14:15], v[170:171], v[184:185] op_sel_hi:[1,0,1]
	ds_read_b32 v170, v188 offset:168
	v_cvt_pk_bf16_f32 v183, v14, v15
	buffer_store_dword v183, v20, s[88:91], s62 offen
	v_lshlrev_b32_e32 v186, 16, v50
	v_and_b32_e32 v187, 0xffff0000, v50
	s_waitcnt lgkmcnt(7)
	v_pk_fma_f32 v[14:15], v[14:15], v[172:173], v[186:187] op_sel_hi:[1,0,1]
	ds_read_b32 v172, v188 offset:172
	v_cvt_pk_bf16_f32 v182, v14, v15
	buffer_store_dword v182, v20, s[88:91], s61 offen
	v_lshlrev_b32_e32 v184, 16, v49
	v_and_b32_e32 v185, 0xffff0000, v49
	s_waitcnt lgkmcnt(7)
	v_pk_fma_f32 v[14:15], v[14:15], v[174:175], v[184:185] op_sel_hi:[1,0,1]
	ds_read_b32 v174, v188 offset:176
	v_cvt_pk_bf16_f32 v183, v14, v15
	buffer_store_dword v183, v20, s[88:91], s60 offen
	v_lshlrev_b32_e32 v186, 16, v48
	v_and_b32_e32 v187, 0xffff0000, v48
	s_waitcnt lgkmcnt(7)
	v_pk_fma_f32 v[14:15], v[14:15], v[176:177], v[186:187] op_sel_hi:[1,0,1]
	ds_read_b32 v176, v188 offset:180
	v_cvt_pk_bf16_f32 v182, v14, v15
	buffer_store_dword v182, v20, s[88:91], s59 offen
	v_lshlrev_b32_e32 v184, 16, v47
	v_and_b32_e32 v185, 0xffff0000, v47
	s_waitcnt lgkmcnt(7)
	v_pk_fma_f32 v[14:15], v[14:15], v[178:179], v[184:185] op_sel_hi:[1,0,1]
	ds_read_b32 v178, v188 offset:184
	v_cvt_pk_bf16_f32 v183, v14, v15
	buffer_store_dword v183, v20, s[88:91], s58 offen
	v_lshlrev_b32_e32 v186, 16, v46
	v_and_b32_e32 v187, 0xffff0000, v46
	s_waitcnt lgkmcnt(7)
	v_pk_fma_f32 v[14:15], v[14:15], v[180:181], v[186:187] op_sel_hi:[1,0,1]
	ds_read_b32 v180, v188 offset:188
	v_cvt_pk_bf16_f32 v182, v14, v15
	buffer_store_dword v182, v20, s[88:91], s57 offen
	v_lshlrev_b32_e32 v184, 16, v45
	v_and_b32_e32 v185, 0xffff0000, v45
	s_waitcnt lgkmcnt(7)
	v_pk_fma_f32 v[14:15], v[14:15], v[166:167], v[184:185] op_sel_hi:[1,0,1]
	ds_read_b32 v166, v188 offset:192
	v_cvt_pk_bf16_f32 v183, v14, v15
	buffer_store_dword v183, v20, s[88:91], s56 offen
	v_lshlrev_b32_e32 v186, 16, v44
	v_and_b32_e32 v187, 0xffff0000, v44
	s_waitcnt lgkmcnt(7)
	v_pk_fma_f32 v[14:15], v[14:15], v[168:169], v[186:187] op_sel_hi:[1,0,1]
	ds_read_b32 v168, v188 offset:196
	v_cvt_pk_bf16_f32 v182, v14, v15
	buffer_store_dword v182, v20, s[88:91], s55 offen
	v_lshlrev_b32_e32 v184, 16, v43
	v_and_b32_e32 v185, 0xffff0000, v43
	s_waitcnt lgkmcnt(7)
	v_pk_fma_f32 v[14:15], v[14:15], v[170:171], v[184:185] op_sel_hi:[1,0,1]
	ds_read_b32 v170, v188 offset:200
	v_cvt_pk_bf16_f32 v183, v14, v15
	buffer_store_dword v183, v20, s[88:91], s54 offen
	v_lshlrev_b32_e32 v186, 16, v42
	v_and_b32_e32 v187, 0xffff0000, v42
	s_waitcnt lgkmcnt(7)
	v_pk_fma_f32 v[14:15], v[14:15], v[172:173], v[186:187] op_sel_hi:[1,0,1]
	ds_read_b32 v172, v188 offset:204
	v_cvt_pk_bf16_f32 v182, v14, v15
	buffer_store_dword v182, v20, s[88:91], s53 offen
	v_lshlrev_b32_e32 v184, 16, v41
	v_and_b32_e32 v185, 0xffff0000, v41
	s_waitcnt lgkmcnt(7)
	v_pk_fma_f32 v[14:15], v[14:15], v[174:175], v[184:185] op_sel_hi:[1,0,1]
	ds_read_b32 v174, v188 offset:208
	v_cvt_pk_bf16_f32 v183, v14, v15
	buffer_store_dword v183, v20, s[88:91], s52 offen
	v_lshlrev_b32_e32 v186, 16, v40
	v_and_b32_e32 v187, 0xffff0000, v40
	s_waitcnt lgkmcnt(7)
	v_pk_fma_f32 v[14:15], v[14:15], v[176:177], v[186:187] op_sel_hi:[1,0,1]
	ds_read_b32 v176, v188 offset:212
	v_cvt_pk_bf16_f32 v182, v14, v15
	buffer_store_dword v182, v20, s[88:91], s51 offen
	v_lshlrev_b32_e32 v184, 16, v39
	v_and_b32_e32 v185, 0xffff0000, v39
	s_waitcnt lgkmcnt(7)
	v_pk_fma_f32 v[14:15], v[14:15], v[178:179], v[184:185] op_sel_hi:[1,0,1]
	ds_read_b32 v178, v188 offset:216
	v_cvt_pk_bf16_f32 v183, v14, v15
	buffer_store_dword v183, v20, s[88:91], s50 offen
	v_lshlrev_b32_e32 v186, 16, v38
	v_and_b32_e32 v187, 0xffff0000, v38
	s_waitcnt lgkmcnt(7)
	v_pk_fma_f32 v[14:15], v[14:15], v[180:181], v[186:187] op_sel_hi:[1,0,1]
	ds_read_b32 v180, v188 offset:220
	v_cvt_pk_bf16_f32 v182, v14, v15
	buffer_store_dword v182, v20, s[88:91], s49 offen
	v_lshlrev_b32_e32 v184, 16, v37
	v_and_b32_e32 v185, 0xffff0000, v37
	s_waitcnt lgkmcnt(7)
	v_pk_fma_f32 v[14:15], v[14:15], v[166:167], v[184:185] op_sel_hi:[1,0,1]
	ds_read_b32 v166, v188 offset:224
	v_cvt_pk_bf16_f32 v183, v14, v15
	buffer_store_dword v183, v20, s[88:91], s35 offen
	v_lshlrev_b32_e32 v186, 16, v36
	v_and_b32_e32 v187, 0xffff0000, v36
	s_waitcnt lgkmcnt(7)
	v_pk_fma_f32 v[14:15], v[14:15], v[168:169], v[186:187] op_sel_hi:[1,0,1]
	ds_read_b32 v168, v188 offset:228
	v_cvt_pk_bf16_f32 v182, v14, v15
	buffer_store_dword v182, v20, s[88:91], s34 offen
	v_lshlrev_b32_e32 v184, 16, v35
	v_and_b32_e32 v185, 0xffff0000, v35
	s_waitcnt lgkmcnt(7)
	v_pk_fma_f32 v[14:15], v[14:15], v[170:171], v[184:185] op_sel_hi:[1,0,1]
	ds_read_b32 v170, v188 offset:232
	v_cvt_pk_bf16_f32 v183, v14, v15
	buffer_store_dword v183, v20, s[88:91], s42 offen
	v_lshlrev_b32_e32 v186, 16, v34
	v_and_b32_e32 v187, 0xffff0000, v34
	s_waitcnt lgkmcnt(7)
	v_pk_fma_f32 v[14:15], v[14:15], v[172:173], v[186:187] op_sel_hi:[1,0,1]
	ds_read_b32 v172, v188 offset:236
	v_cvt_pk_bf16_f32 v182, v14, v15
	buffer_store_dword v182, v20, s[88:91], s40 offen
	v_lshlrev_b32_e32 v184, 16, v33
	v_and_b32_e32 v185, 0xffff0000, v33
	s_waitcnt lgkmcnt(7)
	v_pk_fma_f32 v[14:15], v[14:15], v[174:175], v[184:185] op_sel_hi:[1,0,1]
	ds_read_b32 v174, v188 offset:240
	v_cvt_pk_bf16_f32 v183, v14, v15
	buffer_store_dword v183, v20, s[88:91], s36 offen
	v_lshlrev_b32_e32 v186, 16, v32
	v_and_b32_e32 v187, 0xffff0000, v32
	s_waitcnt lgkmcnt(7)
	v_pk_fma_f32 v[14:15], v[14:15], v[176:177], v[186:187] op_sel_hi:[1,0,1]
	ds_read_b32 v176, v188 offset:244
	v_cvt_pk_bf16_f32 v182, v14, v15
	buffer_store_dword v182, v20, s[88:91], s38 offen
	v_lshlrev_b32_e32 v184, 16, v31
	v_and_b32_e32 v185, 0xffff0000, v31
	s_waitcnt lgkmcnt(7)
	v_pk_fma_f32 v[14:15], v[14:15], v[178:179], v[184:185] op_sel_hi:[1,0,1]
	ds_read_b32 v178, v188 offset:248
	v_cvt_pk_bf16_f32 v183, v14, v15
	buffer_store_dword v183, v20, s[88:91], s22 offen
	v_lshlrev_b32_e32 v186, 16, v30
	v_and_b32_e32 v187, 0xffff0000, v30
	s_waitcnt lgkmcnt(7)
	v_pk_fma_f32 v[14:15], v[14:15], v[180:181], v[186:187] op_sel_hi:[1,0,1]
	ds_read_b32 v180, v188 offset:252
	v_cvt_pk_bf16_f32 v182, v14, v15
	buffer_store_dword v182, v20, s[88:91], s2 offen
	v_lshlrev_b32_e32 v184, 16, v29
	v_and_b32_e32 v185, 0xffff0000, v29
	s_waitcnt lgkmcnt(7)
	v_pk_fma_f32 v[14:15], v[14:15], v[166:167], v[184:185] op_sel_hi:[1,0,1]
	s_nop 0
	v_cvt_pk_bf16_f32 v183, v14, v15
	buffer_store_dword v183, v20, s[88:91], s0 offen
	v_lshlrev_b32_e32 v186, 16, v28
	v_and_b32_e32 v187, 0xffff0000, v28
	s_waitcnt lgkmcnt(6)
	v_pk_fma_f32 v[14:15], v[14:15], v[168:169], v[186:187] op_sel_hi:[1,0,1]
	s_nop 0
	v_cvt_pk_bf16_f32 v182, v14, v15
	buffer_store_dword v182, v20, s[88:91], s48 offen
	v_lshlrev_b32_e32 v184, 16, v26
	v_and_b32_e32 v185, 0xffff0000, v26
	s_waitcnt lgkmcnt(5)
	v_pk_fma_f32 v[14:15], v[14:15], v[170:171], v[184:185] op_sel_hi:[1,0,1]
	s_nop 0
	v_cvt_pk_bf16_f32 v183, v14, v15
	buffer_store_dword v183, v20, s[88:91], s46 offen
	v_lshlrev_b32_e32 v186, 16, v25
	v_and_b32_e32 v187, 0xffff0000, v25
	s_waitcnt lgkmcnt(4)
	v_pk_fma_f32 v[14:15], v[14:15], v[172:173], v[186:187] op_sel_hi:[1,0,1]
	s_nop 0
	v_cvt_pk_bf16_f32 v182, v14, v15
	buffer_store_dword v182, v20, s[88:91], s92 offen
	v_lshlrev_b32_e32 v184, 16, v24
	v_and_b32_e32 v185, 0xffff0000, v24
	s_waitcnt lgkmcnt(3)
	v_pk_fma_f32 v[14:15], v[14:15], v[174:175], v[184:185] op_sel_hi:[1,0,1]
	s_nop 0
	v_cvt_pk_bf16_f32 v183, v14, v15
	buffer_store_dword v183, v20, s[88:91], s95 offen
	v_lshlrev_b32_e32 v186, 16, v23
	v_and_b32_e32 v187, 0xffff0000, v23
	s_waitcnt lgkmcnt(2)
	v_pk_fma_f32 v[14:15], v[14:15], v[176:177], v[186:187] op_sel_hi:[1,0,1]
	s_nop 0
	v_cvt_pk_bf16_f32 v182, v14, v15
	buffer_store_dword v182, v20, s[88:91], s4 offen
	v_lshlrev_b32_e32 v184, 16, v21
	v_and_b32_e32 v185, 0xffff0000, v21
	s_waitcnt lgkmcnt(1)
	v_pk_fma_f32 v[14:15], v[14:15], v[178:179], v[184:185] op_sel_hi:[1,0,1]
	s_nop 0
	v_cvt_pk_bf16_f32 v183, v14, v15
	buffer_store_dword v183, v20, s[88:91], s26 offen
	v_lshlrev_b32_e32 v186, 16, v22
	v_and_b32_e32 v187, 0xffff0000, v22
	s_waitcnt lgkmcnt(0)
	v_pk_fma_f32 v[14:15], v[14:15], v[180:181], v[186:187] op_sel_hi:[1,0,1]
.Lscan_done:
	s_mov_b32 s72, 0xfc2757d1
	s_mov_b32 s73, 0x4e441529
	s_movk_i32 s97, 0x1ff
	v_readlane_b32 s84, v253, 43
	v_readlane_b32 s85, v253, 44
	v_readlane_b32 s86, v253, 45
	v_readlane_b32 s87, v253, 46
	v_readlane_b32 s96, v253, 47
	s_movk_i32 s71, 0x1f8
	s_mov_b32 s17, 0x1c000
	s_movk_i32 s70, 0x6000
	s_mov_b32 s18, 0x14000
	s_mov_b32 s27, 0xc000
	s_mov_b32 s19, 0x8000
	s_movk_i32 s68, 0x2000
	s_movk_i32 s69, 0x4000
	v_readlane_b32 s6, v253, 48
	v_readlane_b32 s7, v253, 49
	v_readlane_b32 s52, v253, 26
	s_movk_i32 s12, 0x1000
	s_mov_b32 s13, 0xbfb8aa3b
	v_readlane_b32 s54, v253, 28
	v_readlane_b32 s55, v253, 29
	v_readlane_b32 s58, v253, 32
	v_readlane_b32 s59, v253, 33
	v_readlane_b32 s60, v253, 34
	v_readlane_b32 s61, v253, 35
	v_readlane_b32 s62, v253, 36
	v_readlane_b32 s63, v253, 37
	v_readlane_b32 s64, v253, 38
	v_readlane_b32 s65, v253, 39
	v_readlane_b32 s66, v253, 40
	v_readlane_b32 s67, v253, 41
	v_readlane_b32 s53, v253, 27
	v_readlane_b32 s56, v253, 30
	v_readlane_b32 s57, v253, 31
	s_mov_b64 s[50:51], s[6:7]
	s_mov_b32 s92, s74
	s_mov_b32 s74, 0xa2f9836e
	s_mov_b32 s95, s75
	s_mov_b32 s75, 0x3fc90fda
	s_mov_b32 s93, 64
	s_mov_b64 s[30:31], 0
	s_and_b64 vcc, exec, s[28:29]
	s_cbranch_vccnz .LBB0_31
	s_branch .LBB0_62

.LBB0_375:
	s_and_b32 s0, s22, 0x3fffffc
	s_bfe_u32 s1, s89, 0x10007
	s_or_b32 s0, s0, s1
	s_lshl_b32 s1, s22, 5
	v_lshl_or_b32 v10, s0, 6, v189
	v_and_or_b32 v1, s1, 32, v188
	s_add_i32 s0, 0, 0x22800
	v_lshl_add_u32 v11, v1, 5, s0
	ds_read_b128 v[6:9], v11
	ds_read_b128 v[12:15], v11 offset:16
	v_readlane_b32 s4, v251, 55
	v_readlane_b32 s5, v251, 56
	s_movk_i32 s1, 0x2800
	s_waitcnt lgkmcnt(1)
	v_mov_b32_e32 v16, v6
	s_waitcnt lgkmcnt(0)
	v_mov_b32_e32 v17, v12
	v_mov_b32_e32 v12, v7
	v_pk_add_f32 v[6:7], v[16:17], v[12:13]
	v_mov_b32_e32 v12, v8
	v_mov_b32_e32 v13, v14
	v_mov_b32_e32 v14, v9
	v_pk_add_f32 v[8:9], v[12:13], v[14:15]
	v_mov_b64_e32 v[14:15], s[4:5]
	v_pk_add_f32 v[6:7], v[6:7], v[8:9]
	v_readlane_b32 s6, v254, 53
	v_add_f32_e32 v6, v6, v7
	v_fmamk_f32 v6, v6, 0x3b000000, v223
	v_rsq_f32_e32 v12, v6
	v_or_b32_e32 v6, s88, v1
	v_mad_i64_i32 v[6:7], s[4:5], v6, s1, v[14:15]
	s_mov_b64 s[4:5], 0x1e00
	v_ashrrev_i32_e32 v11, 31, v10
	v_readlane_b32 s7, v254, 54
	v_lshl_add_u64 v[8:9], v[6:7], 0, s[4:5]
	v_pk_mul_f32 v[20:21], v[170:171], v[12:13] op_sel_hi:[1,0]
	v_lshl_add_u64 v[6:7], v[10:11], 2, s[6:7]
	global_load_dwordx4 v[50:53], v[6:7], off
	global_load_dwordx4 v[54:57], v[6:7], off offset:64
	global_load_dwordx4 v[58:61], v[6:7], off offset:128
	global_load_dwordx4 v[62:65], v[6:7], off offset:192
	global_load_dwordx4 v[66:69], v[6:7], off offset:512
	global_load_dwordx4 v[70:73], v[6:7], off offset:576
	global_load_dwordx4 v[74:77], v[6:7], off offset:640
	global_load_dwordx4 v[78:81], v[6:7], off offset:704
	v_or_b32_e32 v1, 16, v1
	v_readlane_b32 s50, v253, 48
	v_readlane_b32 s52, v253, 26
	v_readlane_b32 s51, v253, 49
	s_movk_i32 s69, 0x4000
	s_movk_i32 s68, 0x2000
	s_mov_b32 s19, 0x8000
	s_mov_b32 s27, 0xc000
	s_mov_b32 s18, 0x14000
	s_mov_b32 s17, 0x1c000
	s_movk_i32 s12, 0x1000
	s_movk_i32 s70, 0x6000
	s_mov_b32 s13, 0xbfb8aa3b
	s_movk_i32 s71, 0x1f8
	s_mov_b64 s[14:15], 0x1000
	s_mov_b64 s[42:43], 0x60
	v_readlane_b32 s60, v253, 34
	v_readlane_b32 s61, v253, 35
	v_readlane_b32 s62, v253, 36
	v_readlane_b32 s63, v253, 37
	v_readlane_b32 s53, v253, 27
	v_readlane_b32 s54, v253, 28
	v_readlane_b32 s55, v253, 29
	v_readlane_b32 s56, v253, 30
	v_readlane_b32 s57, v253, 31
	v_readlane_b32 s58, v253, 32
	v_readlane_b32 s59, v253, 33
	v_readlane_b32 s64, v253, 38
	v_readlane_b32 s65, v253, 39
	v_readlane_b32 s66, v253, 40
	v_readlane_b32 s67, v253, 41
	s_waitcnt vmcnt(0)
	v_mov_b64_e32 v[16:17], v[50:51]
	v_mov_b64_e32 v[18:19], v[52:53]
	v_mov_b32_e32 v24, v16
	v_mov_b32_e32 v25, v18
	v_pk_mul_f32 v[20:21], v[24:25], v[20:21]
	v_pk_mul_f32 v[24:25], v[168:169], v[12:13] op_sel_hi:[1,0]
	v_mov_b32_e32 v18, v17
	v_pk_mul_f32 v[16:17], v[18:19], v[24:25]
	s_nop 0
	v_cvt_pk_bf16_f32 v16, v20, v16
	v_and_b32_sdwa v13, v21, v227 dst_sel:DWORD dst_unused:UNUSED_PAD src0_sel:WORD_1 src1_sel:DWORD
	v_cvt_pk_bf16_f32 v17, v17, v17
	v_add3_u32 v13, v21, v13, s94
	v_and_b32_e32 v17, 0xffff0000, v17
	v_lshlrev_b64 v[18:19], 1, v[10:11]
	v_or_b32_sdwa v17, v17, v13 dst_sel:DWORD dst_unused:UNUSED_PAD src0_sel:DWORD src1_sel:WORD_1
	v_lshl_add_u64 v[20:21], v[8:9], 0, v[18:19]
	global_store_dwordx2 v[20:21], v[16:17], off
	v_pk_mul_f32 v[20:21], v[152:153], v[12:13] op_sel_hi:[1,0]
	v_or_b32_e32 v16, 16, v10
	v_ashrrev_i32_e32 v17, 31, v16
	v_mov_b64_e32 v[30:31], v[54:55]
	v_mov_b64_e32 v[32:33], v[56:57]
	v_mov_b32_e32 v24, v30
	v_mov_b32_e32 v25, v32
	v_pk_mul_f32 v[20:21], v[24:25], v[20:21]
	v_pk_mul_f32 v[24:25], v[150:151], v[12:13] op_sel_hi:[1,0]
	v_mov_b32_e32 v32, v31
	v_pk_mul_f32 v[24:25], v[32:33], v[24:25]
	v_and_b32_sdwa v13, v20, v227 dst_sel:DWORD dst_unused:UNUSED_PAD src0_sel:WORD_1 src1_sel:DWORD
	v_add3_u32 v13, v20, v13, s94
	v_cvt_pk_bf16_f32 v25, v21, v25
	v_cvt_pk_bf16_f32 v21, v24, v24
	v_and_b32_e32 v21, 0xffff0000, v21
	v_or_b32_sdwa v24, v21, v13 dst_sel:DWORD dst_unused:UNUSED_PAD src0_sel:DWORD src1_sel:WORD_1
	v_lshlrev_b64 v[20:21], 1, v[16:17]
	v_lshl_add_u64 v[16:17], v[8:9], 0, v[20:21]
	global_store_dwordx2 v[16:17], v[24:25], off
	v_pk_mul_f32 v[24:25], v[148:149], v[12:13] op_sel_hi:[1,0]
	v_or_b32_e32 v16, 32, v10
	v_ashrrev_i32_e32 v17, 31, v16
	v_mov_b64_e32 v[30:31], v[58:59]
	v_mov_b64_e32 v[32:33], v[60:61]
	v_mov_b32_e32 v38, v30
	v_mov_b32_e32 v39, v32
	v_pk_mul_f32 v[24:25], v[38:39], v[24:25]
	v_pk_mul_f32 v[38:39], v[146:147], v[12:13] op_sel_hi:[1,0]
	v_mov_b32_e32 v32, v31
	v_pk_mul_f32 v[30:31], v[32:33], v[38:39]
	v_and_b32_sdwa v13, v24, v227 dst_sel:DWORD dst_unused:UNUSED_PAD src0_sel:WORD_1 src1_sel:DWORD
	v_add3_u32 v13, v24, v13, s94
	v_cvt_pk_bf16_f32 v31, v25, v31
	v_cvt_pk_bf16_f32 v25, v30, v30
	v_and_b32_e32 v25, 0xffff0000, v25
	v_or_b32_sdwa v30, v25, v13 dst_sel:DWORD dst_unused:UNUSED_PAD src0_sel:DWORD src1_sel:WORD_1
	v_lshlrev_b64 v[24:25], 1, v[16:17]
	v_lshl_add_u64 v[16:17], v[8:9], 0, v[24:25]
	global_store_dwordx2 v[16:17], v[30:31], off
	v_pk_mul_f32 v[38:39], v[136:137], v[12:13] op_sel_hi:[1,0]
	v_or_b32_e32 v16, 48, v10
	v_ashrrev_i32_e32 v17, 31, v16
	v_mov_b64_e32 v[30:31], v[62:63]
	v_mov_b64_e32 v[32:33], v[64:65]
	v_mov_b32_e32 v40, v30
	v_mov_b32_e32 v41, v32
	v_pk_mul_f32 v[38:39], v[38:39], v[40:41]
	v_pk_mul_f32 v[40:41], v[134:135], v[12:13] op_sel_hi:[1,0]
	v_mov_b32_e32 v32, v31
	v_pk_mul_f32 v[30:31], v[40:41], v[32:33]
	s_nop 0
	v_cvt_pk_bf16_f32 v33, v39, v31
	v_cvt_pk_bf16_f32 v32, v38, v30
	v_lshlrev_b64 v[30:31], 1, v[16:17]
	v_lshl_add_u64 v[16:17], v[8:9], 0, v[30:31]
	global_store_dwordx2 v[16:17], v[32:33], off
	v_lshl_add_u32 v11, v1, 5, s0
	ds_read_b128 v[38:41], v11
	ds_read_b128 v[46:49], v11 offset:16
	v_or_b32_e32 v1, s88, v1
	v_mad_i64_i32 v[14:15], s[0:1], v1, s1, v[14:15]
	s_waitcnt lgkmcnt(1)
	v_mov_b32_e32 v16, v38
	s_waitcnt lgkmcnt(0)
	v_mov_b32_e32 v17, v46
	v_mov_b32_e32 v46, v39
	v_mov_b32_e32 v32, v40
	v_mov_b32_e32 v33, v48
	v_mov_b32_e32 v48, v41
	v_pk_add_f32 v[16:17], v[16:17], v[46:47]
	v_pk_add_f32 v[32:33], v[32:33], v[48:49]
	v_lshl_add_u64 v[14:15], v[14:15], 0, s[4:5]
	v_pk_add_f32 v[16:17], v[16:17], v[32:33]
	v_lshl_add_u64 v[18:19], v[14:15], 0, v[18:19]
	v_add_f32_e32 v11, v16, v17
	v_fmamk_f32 v11, v11, 0x3b000000, v223
	v_rsq_f32_e32 v16, v11
	v_lshl_add_u64 v[20:21], v[14:15], 0, v[20:21]
	v_pk_mul_f32 v[32:33], v[132:133], v[16:17] op_sel_hi:[1,0]
	v_mov_b64_e32 v[38:39], v[50:51]
	v_mov_b64_e32 v[40:41], v[52:53]
	v_mov_b32_e32 v46, v38
	v_mov_b32_e32 v47, v40
	v_pk_mul_f32 v[32:33], v[46:47], v[32:33]
	v_pk_mul_f32 v[46:47], v[130:131], v[16:17] op_sel_hi:[1,0]
	v_mov_b32_e32 v40, v39
	v_pk_mul_f32 v[38:39], v[40:41], v[46:47]
	s_nop 0
	v_cvt_pk_bf16_f32 v33, v33, v39
	v_cvt_pk_bf16_f32 v17, v38, v38
	v_cvt_pk_bf16_f32 v11, v32, v32
	v_and_b32_e32 v17, 0xffff0000, v17
	v_or_b32_sdwa v32, v17, v11 dst_sel:DWORD dst_unused:UNUSED_PAD src0_sel:DWORD src1_sel:WORD_1
	global_store_dwordx2 v[18:19], v[32:33], off
	v_pk_mul_f32 v[18:19], v[128:129], v[16:17] op_sel_hi:[1,0]
	v_mov_b64_e32 v[38:39], v[54:55]
	v_mov_b64_e32 v[40:41], v[56:57]
	v_mov_b32_e32 v32, v38
	v_mov_b32_e32 v33, v40
	v_pk_mul_f32 v[18:19], v[32:33], v[18:19]
	v_pk_mul_f32 v[32:33], v[126:127], v[16:17] op_sel_hi:[1,0]
	v_mov_b32_e32 v40, v39
	v_pk_mul_f32 v[32:33], v[40:41], v[32:33]
	s_nop 0
	v_cvt_pk_bf16_f32 v19, v19, v33
	v_cvt_pk_bf16_f32 v17, v32, v32
	v_cvt_pk_bf16_f32 v11, v18, v18
	v_and_b32_e32 v17, 0xffff0000, v17
	v_or_b32_sdwa v18, v17, v11 dst_sel:DWORD dst_unused:UNUSED_PAD src0_sel:DWORD src1_sel:WORD_1
	global_store_dwordx2 v[20:21], v[18:19], off
	v_pk_mul_f32 v[32:33], v[124:125], v[16:17] op_sel_hi:[1,0]
	v_mov_b64_e32 v[18:19], v[58:59]
	v_mov_b64_e32 v[20:21], v[60:61]
	v_mov_b32_e32 v38, v18
	v_mov_b32_e32 v39, v20
	v_pk_mul_f32 v[32:33], v[38:39], v[32:33]
	v_pk_mul_f32 v[38:39], v[122:123], v[16:17] op_sel_hi:[1,0]
	v_mov_b32_e32 v20, v19
	v_pk_mul_f32 v[18:19], v[20:21], v[38:39]
	s_nop 0
	v_cvt_pk_bf16_f32 v19, v33, v19
	v_cvt_pk_bf16_f32 v17, v18, v18
	v_cvt_pk_bf16_f32 v11, v32, v32
	v_and_b32_e32 v17, 0xffff0000, v17
	v_or_b32_sdwa v18, v17, v11 dst_sel:DWORD dst_unused:UNUSED_PAD src0_sel:DWORD src1_sel:WORD_1
	v_lshl_add_u64 v[20:21], v[14:15], 0, v[24:25]
	global_store_dwordx2 v[20:21], v[18:19], off
	v_pk_mul_f32 v[24:25], v[120:121], v[16:17] op_sel_hi:[1,0]
	v_mov_b64_e32 v[18:19], v[62:63]
	v_mov_b64_e32 v[20:21], v[64:65]
	v_mov_b32_e32 v32, v18
	v_mov_b32_e32 v33, v20
	v_pk_mul_f32 v[24:25], v[24:25], v[32:33]
	v_pk_mul_f32 v[32:33], v[118:119], v[16:17] op_sel_hi:[1,0]
	v_mov_b32_e32 v20, v19
	v_pk_mul_f32 v[18:19], v[32:33], v[20:21]
	s_nop 0
	v_cvt_pk_bf16_f32 v18, v24, v18
	v_cvt_pk_bf16_f32 v13, v19, v19
	v_cvt_pk_bf16_f32 v1, v25, v25
	v_and_b32_e32 v13, 0xffff0000, v13
	v_or_b32_sdwa v19, v13, v1 dst_sel:DWORD dst_unused:UNUSED_PAD src0_sel:DWORD src1_sel:WORD_1
	v_lshl_add_u64 v[20:21], v[14:15], 0, v[30:31]
	global_store_dwordx2 v[20:21], v[18:19], off
	v_pk_mul_f32 v[30:31], v[154:155], v[12:13] op_sel_hi:[1,0]
	v_or_b32_e32 v24, 0x80, v10
	v_ashrrev_i32_e32 v25, 31, v24
	v_mov_b64_e32 v[18:19], v[66:67]
	v_mov_b64_e32 v[20:21], v[68:69]
	v_mov_b32_e32 v32, v18
	v_mov_b32_e32 v33, v20
	v_pk_mul_f32 v[30:31], v[30:31], v[32:33]
	v_pk_mul_f32 v[32:33], v[116:117], v[12:13] op_sel_hi:[1,0]
	v_mov_b32_e32 v20, v19
	v_pk_mul_f32 v[18:19], v[32:33], v[20:21]
	s_nop 0
	v_cvt_pk_bf16_f32 v20, v30, v18
	v_cvt_pk_bf16_f32 v13, v19, v19
	v_cvt_pk_bf16_f32 v1, v31, v31
	v_and_b32_e32 v13, 0xffff0000, v13
	v_lshlrev_b64 v[18:19], 1, v[24:25]
	v_or_b32_sdwa v21, v13, v1 dst_sel:DWORD dst_unused:UNUSED_PAD src0_sel:DWORD src1_sel:WORD_1
	v_lshl_add_u64 v[24:25], v[8:9], 0, v[18:19]
	global_store_dwordx2 v[24:25], v[20:21], off
	v_pk_mul_f32 v[24:25], v[114:115], v[12:13] op_sel_hi:[1,0]
	v_or_b32_e32 v20, 0x90, v10
	v_ashrrev_i32_e32 v21, 31, v20
	v_lshlrev_b64 v[20:21], 1, v[20:21]
	v_mov_b64_e32 v[30:31], v[70:71]
	v_mov_b64_e32 v[32:33], v[72:73]
	v_mov_b32_e32 v38, v30
	v_mov_b32_e32 v39, v32
	v_pk_mul_f32 v[24:25], v[24:25], v[38:39]
	v_pk_mul_f32 v[38:39], v[112:113], v[12:13] op_sel_hi:[1,0]
	v_mov_b32_e32 v32, v31
	v_pk_mul_f32 v[30:31], v[38:39], v[32:33]
	s_nop 0
	v_cvt_pk_bf16_f32 v24, v24, v30
	v_cvt_pk_bf16_f32 v13, v31, v31
	v_cvt_pk_bf16_f32 v1, v25, v25
	v_and_b32_e32 v13, 0xffff0000, v13
	v_or_b32_sdwa v25, v13, v1 dst_sel:DWORD dst_unused:UNUSED_PAD src0_sel:DWORD src1_sel:WORD_1
	v_lshl_add_u64 v[30:31], v[8:9], 0, v[20:21]
	global_store_dwordx2 v[30:31], v[24:25], off
	v_pk_mul_f32 v[38:39], v[110:111], v[12:13] op_sel_hi:[1,0]
	v_or_b32_e32 v24, 0xa0, v10
	v_ashrrev_i32_e32 v25, 31, v24
	v_lshlrev_b64 v[24:25], 1, v[24:25]
	v_or_b32_e32 v10, 0xb0, v10
	v_mov_b64_e32 v[30:31], v[74:75]
	v_mov_b64_e32 v[32:33], v[76:77]
	v_mov_b32_e32 v40, v30
	v_mov_b32_e32 v41, v32
	v_pk_mul_f32 v[38:39], v[38:39], v[40:41]
	v_pk_mul_f32 v[40:41], v[108:109], v[12:13] op_sel_hi:[1,0]
	v_mov_b32_e32 v32, v31
	v_pk_mul_f32 v[30:31], v[40:41], v[32:33]
	s_nop 0
	v_cvt_pk_bf16_f32 v30, v38, v30
	v_cvt_pk_bf16_f32 v13, v31, v31
	v_cvt_pk_bf16_f32 v1, v39, v39
	v_and_b32_e32 v13, 0xffff0000, v13
	v_or_b32_sdwa v31, v13, v1 dst_sel:DWORD dst_unused:UNUSED_PAD src0_sel:DWORD src1_sel:WORD_1
	v_lshl_add_u64 v[32:33], v[8:9], 0, v[24:25]
	global_store_dwordx2 v[32:33], v[30:31], off
	v_pk_mul_f32 v[38:39], v[106:107], v[12:13] op_sel_hi:[1,0]
	v_pk_mul_f32 v[12:13], v[102:103], v[12:13] op_sel_hi:[1,0]
	v_ashrrev_i32_e32 v11, 31, v10
	v_lshlrev_b64 v[10:11], 1, v[10:11]
	v_lshl_add_u64 v[8:9], v[8:9], 0, v[10:11]
	v_mov_b64_e32 v[30:31], v[78:79]
	v_mov_b64_e32 v[32:33], v[80:81]
	v_mov_b32_e32 v41, v32
	v_mov_b32_e32 v32, v31
	v_mov_b32_e32 v40, v30
	v_pk_mul_f32 v[12:13], v[12:13], v[32:33]
	v_pk_mul_f32 v[38:39], v[38:39], v[40:41]
	s_nop 0
	v_cvt_pk_bf16_f32 v13, v39, v13
	v_and_b32_sdwa v17, v38, v227 dst_sel:DWORD dst_unused:UNUSED_PAD src0_sel:WORD_1 src1_sel:DWORD
	v_cvt_pk_bf16_f32 v12, v12, v12
	v_add3_u32 v17, v38, v17, s94
	v_and_b32_e32 v12, 0xffff0000, v12
	v_or_b32_sdwa v12, v12, v17 dst_sel:DWORD dst_unused:UNUSED_PAD src0_sel:DWORD src1_sel:WORD_1
	global_store_dwordx2 v[8:9], v[12:13], off
	v_pk_mul_f32 v[8:9], v[104:105], v[16:17] op_sel_hi:[1,0]
	v_mov_b64_e32 v[30:31], v[66:67]
	v_mov_b64_e32 v[32:33], v[68:69]
	v_mov_b32_e32 v12, v30
	v_mov_b32_e32 v13, v32
	v_pk_mul_f32 v[8:9], v[8:9], v[12:13]
	v_pk_mul_f32 v[12:13], v[44:45], v[16:17] op_sel_hi:[1,0]
	v_mov_b32_e32 v32, v31
	v_pk_mul_f32 v[12:13], v[12:13], v[32:33]
	v_cvt_pk_bf16_f32 v8, v8, v8
	v_cvt_pk_bf16_f32 v9, v9, v13
	v_and_b32_sdwa v17, v12, v227 dst_sel:DWORD dst_unused:UNUSED_PAD src0_sel:WORD_1 src1_sel:DWORD
	v_add3_u32 v12, v12, v17, s94
	v_and_b32_e32 v12, 0xffff0000, v12
	v_or_b32_sdwa v8, v12, v8 dst_sel:DWORD dst_unused:UNUSED_PAD src0_sel:DWORD src1_sel:WORD_1
	v_lshl_add_u64 v[12:13], v[14:15], 0, v[18:19]
	global_store_dwordx2 v[12:13], v[8:9], off
	v_pk_mul_f32 v[8:9], v[42:43], v[16:17] op_sel_hi:[1,0]
	v_mov_b64_e32 v[30:31], v[70:71]
	v_mov_b64_e32 v[32:33], v[72:73]
	v_mov_b32_e32 v12, v30
	v_mov_b32_e32 v13, v32
	v_pk_mul_f32 v[8:9], v[8:9], v[12:13]
	v_pk_mul_f32 v[12:13], v[36:37], v[16:17] op_sel_hi:[1,0]
	v_mov_b32_e32 v32, v31
	v_pk_mul_f32 v[12:13], v[12:13], v[32:33]
	v_cvt_pk_bf16_f32 v8, v8, v8
	v_cvt_pk_bf16_f32 v9, v9, v13
	v_and_b32_sdwa v17, v12, v227 dst_sel:DWORD dst_unused:UNUSED_PAD src0_sel:WORD_1 src1_sel:DWORD
	v_add3_u32 v12, v12, v17, s94
	v_and_b32_e32 v12, 0xffff0000, v12
	v_or_b32_sdwa v8, v12, v8 dst_sel:DWORD dst_unused:UNUSED_PAD src0_sel:DWORD src1_sel:WORD_1
	v_lshl_add_u64 v[12:13], v[14:15], 0, v[20:21]
	global_store_dwordx2 v[12:13], v[8:9], off
	v_pk_mul_f32 v[8:9], v[34:35], v[16:17] op_sel_hi:[1,0]
	v_mov_b64_e32 v[18:19], v[74:75]
	v_mov_b64_e32 v[20:21], v[76:77]
	v_mov_b32_e32 v12, v18
	v_mov_b32_e32 v13, v20
	v_pk_mul_f32 v[8:9], v[8:9], v[12:13]
	v_pk_mul_f32 v[12:13], v[28:29], v[16:17] op_sel_hi:[1,0]
	v_mov_b32_e32 v20, v19
	v_pk_mul_f32 v[12:13], v[12:13], v[20:21]
	v_cvt_pk_bf16_f32 v8, v8, v8
	v_cvt_pk_bf16_f32 v9, v9, v13
	v_and_b32_sdwa v17, v12, v227 dst_sel:DWORD dst_unused:UNUSED_PAD src0_sel:WORD_1 src1_sel:DWORD
	v_add3_u32 v12, v12, v17, s94
	v_and_b32_e32 v12, 0xffff0000, v12
	v_or_b32_sdwa v8, v12, v8 dst_sel:DWORD dst_unused:UNUSED_PAD src0_sel:DWORD src1_sel:WORD_1
	v_lshl_add_u64 v[12:13], v[14:15], 0, v[24:25]
	global_store_dwordx2 v[12:13], v[8:9], off
	v_pk_mul_f32 v[12:13], v[26:27], v[16:17] op_sel_hi:[1,0]
	v_pk_mul_f32 v[16:17], v[22:23], v[16:17] op_sel_hi:[1,0]
	v_mov_b64_e32 v[6:7], v[78:79]
	v_mov_b64_e32 v[8:9], v[80:81]
	v_mov_b32_e32 v18, v6
	v_mov_b32_e32 v19, v8
	v_pk_mul_f32 v[12:13], v[12:13], v[18:19]
	v_mov_b32_e32 v8, v7
	v_pk_mul_f32 v[6:7], v[16:17], v[8:9]
	s_nop 0
	v_cvt_pk_bf16_f32 v6, v12, v6
	v_cvt_pk_bf16_f32 v7, v13, v7
	v_lshl_add_u64 v[8:9], v[14:15], 0, v[10:11]
	global_store_dwordx2 v[8:9], v[6:7], off

.LBB0_388:
	s_and_b64 vcc, exec, s[0:1]
	s_cbranch_vccz .LBB0_392
	s_waitcnt lgkmcnt(0)
	v_mov_b32_e32 v1, v0
	s_ashr_i32 s29, s28, 31
	s_lshl_b32 s88, s28, 6
	v_readlane_b32 s36, v251, 55
	v_readlane_b32 s37, v251, 56
	v_lshlrev_b32_e32 v194, 3, v0
	v_and_b32_e32 v194, 0x1f8, v194
	v_lshlrev_b32_e32 v194, 1, v194
	v_mov_b32_e32 v195, 0
	v_ashrrev_i32_e32 v196, 6, v0
	v_add_u32_e32 v196, s88, v196
	s_movk_i32 s38, 0x2800
	v_mov_b64_e32 v[198:199], s[36:37]
	s_mov_b64 s[44:45], 0x14000
	v_mad_i64_i32 v[200:201], s[40:41], v196, s38, v[198:199]
	v_lshl_add_u64 v[200:201], v[200:201], 0, v[194:195]
	global_load_dwordx4 v[162:165], v[200:201], off offset:3584
	v_lshl_add_u64 v[200:201], v[200:201], 0, s[44:45]
	global_load_dwordx4 v[166:169], v[200:201], off offset:3584
	v_lshl_add_u64 v[200:201], v[200:201], 0, s[44:45]
	global_load_dwordx4 v[170:173], v[200:201], off offset:3584
	v_lshl_add_u64 v[200:201], v[200:201], 0, s[44:45]
	global_load_dwordx4 v[174:177], v[200:201], off offset:3584
	v_lshl_add_u64 v[200:201], v[200:201], 0, s[44:45]
	global_load_dwordx4 v[178:181], v[200:201], off offset:3584
	v_lshl_add_u64 v[200:201], v[200:201], 0, s[44:45]
	global_load_dwordx4 v[182:185], v[200:201], off offset:3584
	v_lshl_add_u64 v[200:201], v[200:201], 0, s[44:45]
	global_load_dwordx4 v[186:189], v[200:201], off offset:3584
	v_lshl_add_u64 v[200:201], v[200:201], 0, s[44:45]
	global_load_dwordx4 v[190:193], v[200:201], off offset:3584
	s_lshl_b64 s[0:1], s[28:29], 11
	v_readlane_b32 s4, v250, 33
	v_lshlrev_b32_e32 v6, 3, v1
	s_add_u32 s0, s4, s0
	v_readlane_b32 s4, v250, 34
	v_and_b32_e32 v11, 0x1f8, v6
	s_addc_u32 s1, s4, s1
	v_lshlrev_b32_e32 v138, 2, v11
	s_waitcnt lgkmcnt(0)
	global_load_dwordx4 v[6:9], v138, s[0:1] offset:16
	global_load_dwordx4 v[14:17], v138, s[0:1]
	v_ashrrev_i32_e32 v1, 3, v1
	v_readlane_b32 s0, v250, 41
	v_and_b32_e32 v1, -8, v1
	v_readlane_b32 s1, v250, 42
	v_add_u32_e32 v10, s88, v1
	s_movk_i32 s4, 0x2800
	v_lshl_add_u64 v[12:13], s[0:1], 0, v[138:139]
	v_readlane_b32 s0, v251, 55
	v_lshlrev_b32_e32 v138, 1, v11
	v_readlane_b32 s1, v251, 56
	v_ashrrev_i32_e32 v11, 31, v10
	v_lshlrev_b64 v[20:21], 11, v[10:11]
	v_lshl_add_u64 v[18:19], s[0:1], 0, v[138:139]
	v_lshl_add_u64 v[20:21], v[12:13], 0, v[20:21]
	v_mad_i64_i32 v[120:121], s[0:1], v10, s4, v[18:19]
	global_load_dwordx4 v[98:101], v[20:21], off offset:16
	global_load_dwordx4 v[124:127], v[20:21], off
	global_load_dwordx4 v[102:105], v[120:121], off
	v_or_b32_e32 v20, 1, v10
	v_ashrrev_i32_e32 v21, 31, v20
	v_lshlrev_b64 v[22:23], 11, v[20:21]
	v_lshl_add_u64 v[22:23], v[12:13], 0, v[22:23]
	v_mad_i64_i32 v[118:119], s[0:1], v20, s4, v[18:19]
	global_load_dwordx4 v[86:89], v[22:23], off offset:16
	global_load_dwordx4 v[94:97], v[22:23], off
	global_load_dwordx4 v[90:93], v[118:119], off
	v_or_b32_e32 v20, 2, v10
	v_ashrrev_i32_e32 v21, 31, v20
	v_lshlrev_b64 v[22:23], 11, v[20:21]
	v_lshl_add_u64 v[22:23], v[12:13], 0, v[22:23]
	v_mad_i64_i32 v[116:117], s[0:1], v20, s4, v[18:19]
	global_load_dwordx4 v[74:77], v[22:23], off offset:16
	global_load_dwordx4 v[82:85], v[22:23], off
	global_load_dwordx4 v[78:81], v[116:117], off
	v_or_b32_e32 v20, 3, v10
	v_ashrrev_i32_e32 v21, 31, v20
	v_lshlrev_b64 v[22:23], 11, v[20:21]
	v_mad_i64_i32 v[114:115], s[0:1], v20, s4, v[18:19]
	v_or_b32_e32 v20, 4, v10
	v_lshl_add_u64 v[22:23], v[12:13], 0, v[22:23]
	v_ashrrev_i32_e32 v21, 31, v20
	global_load_dwordx4 v[62:65], v[22:23], off offset:16
	global_load_dwordx4 v[70:73], v[22:23], off
	v_lshlrev_b64 v[22:23], 11, v[20:21]
	v_mad_i64_i32 v[112:113], s[0:1], v20, s4, v[18:19]
	v_or_b32_e32 v20, 5, v10
	v_lshl_add_u64 v[22:23], v[12:13], 0, v[22:23]
	v_ashrrev_i32_e32 v21, 31, v20
	global_load_dwordx4 v[66:69], v[114:115], off
	global_load_dwordx4 v[50:53], v[22:23], off offset:16
	global_load_dwordx4 v[58:61], v[22:23], off
	v_lshlrev_b64 v[22:23], 11, v[20:21]
	v_mad_i64_i32 v[110:111], s[0:1], v20, s4, v[18:19]
	v_or_b32_e32 v20, 6, v10
	v_lshl_add_u64 v[22:23], v[12:13], 0, v[22:23]
	v_ashrrev_i32_e32 v21, 31, v20
	global_load_dwordx4 v[54:57], v[112:113], off
	global_load_dwordx4 v[38:41], v[22:23], off offset:16
	global_load_dwordx4 v[46:49], v[22:23], off
	v_lshlrev_b64 v[22:23], 11, v[20:21]
	v_mad_i64_i32 v[108:109], s[0:1], v20, s4, v[18:19]
	v_or_b32_e32 v20, 7, v10
	v_ashrrev_i32_e32 v21, 31, v20
	v_lshl_add_u64 v[22:23], v[12:13], 0, v[22:23]
	v_lshlrev_b64 v[10:11], 11, v[20:21]
	global_load_dwordx4 v[42:45], v[110:111], off
	global_load_dwordx4 v[26:29], v[22:23], off offset:16
	global_load_dwordx4 v[34:37], v[22:23], off
	v_lshl_add_u64 v[22:23], v[12:13], 0, v[10:11]
	v_mad_i64_i32 v[106:107], s[0:1], v20, s4, v[18:19]
	global_load_dwordx4 v[30:33], v[108:109], off
	global_load_dwordx4 v[10:13], v[22:23], off offset:16
	s_nop 0
	global_load_dwordx4 v[22:25], v[22:23], off
	s_waitcnt vmcnt(0)
	v_and_b32_e32 v135, 0xffff0000, v126
	v_lshlrev_b32_e32 v122, 16, v102
	v_mul_f32_e32 v1, 0xbfb8aa3b, v122
	v_exp_f32_e32 v1, v1
	v_and_b32_e32 v130, 0xffff0000, v102
	v_lshlrev_b32_e32 v123, 16, v103
	v_and_b32_e32 v131, 0xffff0000, v103
	v_add_f32_e32 v1, 1.0, v1
	v_rcp_f32_e32 v128, v1
	v_mul_f32_e32 v1, 0xbfb8aa3b, v130
	v_exp_f32_e32 v1, v1
	v_lshlrev_b32_e32 v137, 16, v126
	v_mov_b32_e32 v103, v16
	v_lshlrev_b32_e32 v126, 16, v125
	v_add_f32_e32 v1, 1.0, v1
	v_rcp_f32_e32 v132, v1
	v_mul_f32_e32 v1, 0xbfb8aa3b, v123
	v_exp_f32_e32 v1, v1
	v_mov_b32_e32 v16, v15
	v_mov_b32_e32 v102, v14
	v_and_b32_e32 v134, 0xffff0000, v124
	v_add_f32_e32 v1, 1.0, v1
	v_rcp_f32_e32 v129, v1
	v_mul_f32_e32 v1, 0xbfb8aa3b, v131
	v_exp_f32_e32 v1, v1
	v_lshlrev_b32_e32 v136, 16, v124
	v_pk_mul_f32 v[122:123], v[128:129], v[122:123]
	v_and_b32_e32 v129, 0xffff0000, v127
	v_and_b32_e32 v128, 0xffff0000, v125
	v_lshlrev_b32_e32 v127, 16, v127
	v_pk_fma_f32 v[14:15], v[16:17], v[126:127], v[128:129]
	v_add_f32_e32 v1, 1.0, v1
	v_lshlrev_b32_e32 v126, 16, v104
	v_rcp_f32_e32 v133, v1
	v_mul_f32_e32 v1, 0xbfb8aa3b, v126
	v_exp_f32_e32 v1, v1
	v_and_b32_e32 v104, 0xffff0000, v104
	v_lshlrev_b32_e32 v127, 16, v105
	v_pk_mul_f32 v[124:125], v[132:133], v[130:131]
	v_add_f32_e32 v1, 1.0, v1
	v_rcp_f32_e32 v128, v1
	v_mul_f32_e32 v1, 0xbfb8aa3b, v104
	v_exp_f32_e32 v1, v1
	v_and_b32_e32 v105, 0xffff0000, v105
	v_pk_fma_f32 v[134:135], v[102:103], v[136:137], v[134:135]
	v_pk_mul_f32 v[124:125], v[14:15], v[124:125]
	v_add_f32_e32 v1, 1.0, v1
	v_rcp_f32_e32 v130, v1
	v_mul_f32_e32 v1, 0xbfb8aa3b, v127
	v_exp_f32_e32 v1, v1
	v_pk_mul_f32 v[122:123], v[134:135], v[122:123]
	v_and_b32_e32 v133, 0xffff0000, v100
	v_and_b32_e32 v132, 0xffff0000, v98
	v_add_f32_e32 v1, 1.0, v1
	v_rcp_f32_e32 v129, v1
	v_mul_f32_e32 v1, 0xbfb8aa3b, v105
	v_exp_f32_e32 v1, v1
	v_lshlrev_b32_e32 v135, 16, v100
	v_lshlrev_b32_e32 v134, 16, v98
	v_mov_b32_e32 v14, v6
	v_add_f32_e32 v1, 1.0, v1
	v_rcp_f32_e32 v131, v1
	v_mov_b32_e32 v15, v8
	v_pk_fma_f32 v[132:133], v[14:15], v[134:135], v[132:133]
	v_pk_mul_f32 v[126:127], v[128:129], v[126:127]
	v_and_b32_e32 v129, 0xffff0000, v101
	v_and_b32_e32 v128, 0xffff0000, v99
	v_lshlrev_b32_e32 v101, 16, v101
	v_lshlrev_b32_e32 v100, 16, v99
	v_mov_b32_e32 v8, v7
	v_pk_mul_f32 v[126:127], v[132:133], v[126:127]
	v_pk_fma_f32 v[6:7], v[8:9], v[100:101], v[128:129]
	v_pk_mul_f32 v[98:99], v[130:131], v[104:105]
	s_nop 0
	v_pk_mul_f32 v[6:7], v[6:7], v[98:99]
	s_nop 0
	v_cvt_pk_bf16_f32 v100, v126, v6
	v_cvt_pk_bf16_f32 v101, v127, v7
	v_lshlrev_b32_e32 v6, 16, v90
	v_mul_f32_e32 v1, 0xbfb8aa3b, v6
	v_exp_f32_e32 v1, v1
	v_cvt_pk_bf16_f32 v99, v123, v125
	v_cvt_pk_bf16_f32 v98, v122, v124
	v_add_f32_e32 v1, 1.0, v1
	v_and_b32_e32 v90, 0xffff0000, v90
	global_load_dwordx4 v[18:21], v[106:107], off
	global_store_dwordx4 v[120:121], v[98:101], off
	v_lshlrev_b32_e32 v7, 16, v91
	v_and_b32_e32 v91, 0xffff0000, v91
	v_rcp_f32_e32 v98, v1
	v_mul_f32_e32 v1, 0xbfb8aa3b, v90
	v_exp_f32_e32 v1, v1
	v_and_b32_e32 v105, 0xffff0000, v96
	v_lshlrev_b32_e32 v121, 16, v96
	v_lshlrev_b32_e32 v96, 16, v95
	v_add_f32_e32 v1, 1.0, v1
	v_rcp_f32_e32 v100, v1
	v_mul_f32_e32 v1, 0xbfb8aa3b, v7
	v_exp_f32_e32 v1, v1
	v_and_b32_e32 v104, 0xffff0000, v94
	v_lshlrev_b32_e32 v120, 16, v94
	v_pk_fma_f32 v[104:105], v[102:103], v[120:121], v[104:105]
	v_add_f32_e32 v1, 1.0, v1
	v_rcp_f32_e32 v99, v1
	v_mul_f32_e32 v1, 0xbfb8aa3b, v91
	v_exp_f32_e32 v1, v1
	v_pk_mul_f32 v[6:7], v[98:99], v[6:7]
	v_and_b32_e32 v99, 0xffff0000, v97
	v_add_f32_e32 v1, 1.0, v1
	v_rcp_f32_e32 v101, v1
	v_and_b32_e32 v98, 0xffff0000, v95
	v_lshlrev_b32_e32 v97, 16, v97
	v_pk_fma_f32 v[94:95], v[16:17], v[96:97], v[98:99]
	v_pk_mul_f32 v[90:91], v[100:101], v[90:91]
	v_pk_mul_f32 v[6:7], v[104:105], v[6:7]
	v_pk_mul_f32 v[90:91], v[94:95], v[90:91]
	v_lshlrev_b32_e32 v94, 16, v92
	v_mul_f32_e32 v1, 0xbfb8aa3b, v94
	v_exp_f32_e32 v1, v1
	v_and_b32_e32 v92, 0xffff0000, v92
	v_lshlrev_b32_e32 v95, 16, v93
	v_and_b32_e32 v93, 0xffff0000, v93
	v_add_f32_e32 v1, 1.0, v1
	v_rcp_f32_e32 v96, v1
	v_mul_f32_e32 v1, 0xbfb8aa3b, v92
	v_exp_f32_e32 v1, v1
	v_and_b32_e32 v101, 0xffff0000, v88
	v_lshlrev_b32_e32 v105, 16, v88
	v_lshlrev_b32_e32 v88, 16, v87
	v_add_f32_e32 v1, 1.0, v1
	v_rcp_f32_e32 v98, v1
	v_mul_f32_e32 v1, 0xbfb8aa3b, v95
	v_exp_f32_e32 v1, v1
	v_and_b32_e32 v100, 0xffff0000, v86
	v_lshlrev_b32_e32 v104, 16, v86
	v_pk_fma_f32 v[100:101], v[14:15], v[104:105], v[100:101]
	v_add_f32_e32 v1, 1.0, v1
	v_rcp_f32_e32 v97, v1
	v_mul_f32_e32 v1, 0xbfb8aa3b, v93
	v_exp_f32_e32 v1, v1
	v_pk_mul_f32 v[94:95], v[96:97], v[94:95]
	v_and_b32_e32 v97, 0xffff0000, v89
	v_add_f32_e32 v1, 1.0, v1
	v_rcp_f32_e32 v99, v1
	v_and_b32_e32 v96, 0xffff0000, v87
	v_lshlrev_b32_e32 v89, 16, v89
	v_pk_fma_f32 v[86:87], v[8:9], v[88:89], v[96:97]
	v_pk_mul_f32 v[88:89], v[98:99], v[92:93]
	v_pk_mul_f32 v[94:95], v[100:101], v[94:95]
	v_pk_mul_f32 v[86:87], v[86:87], v[88:89]
	s_nop 0
	v_cvt_pk_bf16_f32 v89, v95, v87
	v_cvt_pk_bf16_f32 v87, v7, v91
	v_cvt_pk_bf16_f32 v88, v94, v86
	v_cvt_pk_bf16_f32 v86, v6, v90
	v_lshlrev_b32_e32 v6, 16, v78
	v_mul_f32_e32 v1, 0xbfb8aa3b, v6
	v_exp_f32_e32 v1, v1
	v_and_b32_e32 v78, 0xffff0000, v78
	v_add_f32_e32 v1, 1.0, v1
	global_store_dwordx4 v[118:119], v[86:89], off
	v_lshlrev_b32_e32 v7, 16, v79
	v_and_b32_e32 v79, 0xffff0000, v79
	v_rcp_f32_e32 v86, v1
	v_mul_f32_e32 v1, 0xbfb8aa3b, v78
	v_exp_f32_e32 v1, v1
	v_and_b32_e32 v91, 0xffff0000, v84
	v_lshlrev_b32_e32 v93, 16, v84
	v_lshlrev_b32_e32 v84, 16, v83
	v_add_f32_e32 v1, 1.0, v1
	v_rcp_f32_e32 v88, v1
	v_mul_f32_e32 v1, 0xbfb8aa3b, v7
	v_exp_f32_e32 v1, v1
	v_and_b32_e32 v90, 0xffff0000, v82
	v_lshlrev_b32_e32 v92, 16, v82
	v_pk_fma_f32 v[90:91], v[102:103], v[92:93], v[90:91]
	v_add_f32_e32 v1, 1.0, v1
	v_rcp_f32_e32 v87, v1
	v_mul_f32_e32 v1, 0xbfb8aa3b, v79
	v_exp_f32_e32 v1, v1
	v_pk_mul_f32 v[6:7], v[86:87], v[6:7]
	v_and_b32_e32 v87, 0xffff0000, v85
	v_add_f32_e32 v1, 1.0, v1
	v_rcp_f32_e32 v89, v1
	v_and_b32_e32 v86, 0xffff0000, v83
	v_lshlrev_b32_e32 v85, 16, v85
	v_pk_fma_f32 v[82:83], v[16:17], v[84:85], v[86:87]
	v_pk_mul_f32 v[78:79], v[88:89], v[78:79]
	v_pk_mul_f32 v[6:7], v[90:91], v[6:7]
	v_pk_mul_f32 v[78:79], v[82:83], v[78:79]
	v_lshlrev_b32_e32 v82, 16, v80
	v_mul_f32_e32 v1, 0xbfb8aa3b, v82
	v_exp_f32_e32 v1, v1
	v_and_b32_e32 v80, 0xffff0000, v80
	v_lshlrev_b32_e32 v83, 16, v81
	v_and_b32_e32 v81, 0xffff0000, v81
	v_add_f32_e32 v1, 1.0, v1
	v_rcp_f32_e32 v84, v1
	v_mul_f32_e32 v1, 0xbfb8aa3b, v80
	v_exp_f32_e32 v1, v1
	v_and_b32_e32 v89, 0xffff0000, v76
	v_lshlrev_b32_e32 v91, 16, v76
	v_lshlrev_b32_e32 v76, 16, v75
	v_add_f32_e32 v1, 1.0, v1
	v_rcp_f32_e32 v86, v1
	v_mul_f32_e32 v1, 0xbfb8aa3b, v83
	v_exp_f32_e32 v1, v1
	v_and_b32_e32 v88, 0xffff0000, v74
	v_lshlrev_b32_e32 v90, 16, v74
	v_pk_fma_f32 v[88:89], v[14:15], v[90:91], v[88:89]
	v_add_f32_e32 v1, 1.0, v1
	v_rcp_f32_e32 v85, v1
	v_mul_f32_e32 v1, 0xbfb8aa3b, v81
	v_exp_f32_e32 v1, v1
	v_pk_mul_f32 v[82:83], v[84:85], v[82:83]
	v_and_b32_e32 v85, 0xffff0000, v77
	v_add_f32_e32 v1, 1.0, v1
	v_rcp_f32_e32 v87, v1
	v_and_b32_e32 v84, 0xffff0000, v75
	v_lshlrev_b32_e32 v77, 16, v77
	v_pk_fma_f32 v[74:75], v[8:9], v[76:77], v[84:85]
	v_pk_mul_f32 v[76:77], v[86:87], v[80:81]
	v_pk_mul_f32 v[82:83], v[88:89], v[82:83]
	v_pk_mul_f32 v[74:75], v[74:75], v[76:77]
	s_nop 0
	v_cvt_pk_bf16_f32 v77, v83, v75
	v_cvt_pk_bf16_f32 v75, v7, v79
	v_cvt_pk_bf16_f32 v76, v82, v74
	v_cvt_pk_bf16_f32 v74, v6, v78
	v_lshlrev_b32_e32 v6, 16, v66
	v_mul_f32_e32 v1, 0xbfb8aa3b, v6
	v_exp_f32_e32 v1, v1
	v_and_b32_e32 v66, 0xffff0000, v66
	v_add_f32_e32 v1, 1.0, v1
	global_store_dwordx4 v[116:117], v[74:77], off
	v_lshlrev_b32_e32 v7, 16, v67
	v_and_b32_e32 v67, 0xffff0000, v67
	v_rcp_f32_e32 v74, v1
	v_mul_f32_e32 v1, 0xbfb8aa3b, v66
	v_exp_f32_e32 v1, v1
	v_and_b32_e32 v79, 0xffff0000, v72
	v_lshlrev_b32_e32 v81, 16, v72
	v_lshlrev_b32_e32 v72, 16, v71
	v_add_f32_e32 v1, 1.0, v1
	v_rcp_f32_e32 v76, v1
	v_mul_f32_e32 v1, 0xbfb8aa3b, v7
	v_exp_f32_e32 v1, v1
	v_and_b32_e32 v78, 0xffff0000, v70
	v_lshlrev_b32_e32 v80, 16, v70
	v_pk_fma_f32 v[78:79], v[102:103], v[80:81], v[78:79]
	v_add_f32_e32 v1, 1.0, v1
	v_rcp_f32_e32 v75, v1
	v_mul_f32_e32 v1, 0xbfb8aa3b, v67
	v_exp_f32_e32 v1, v1
	v_pk_mul_f32 v[6:7], v[74:75], v[6:7]
	v_and_b32_e32 v75, 0xffff0000, v73
	v_add_f32_e32 v1, 1.0, v1
	v_rcp_f32_e32 v77, v1
	v_and_b32_e32 v74, 0xffff0000, v71
	v_lshlrev_b32_e32 v73, 16, v73
	v_pk_fma_f32 v[70:71], v[16:17], v[72:73], v[74:75]
	v_pk_mul_f32 v[66:67], v[76:77], v[66:67]
	v_pk_mul_f32 v[6:7], v[78:79], v[6:7]
	v_pk_mul_f32 v[66:67], v[70:71], v[66:67]
	v_lshlrev_b32_e32 v70, 16, v68
	v_mul_f32_e32 v1, 0xbfb8aa3b, v70
	v_exp_f32_e32 v1, v1
	v_and_b32_e32 v68, 0xffff0000, v68
	v_lshlrev_b32_e32 v71, 16, v69
	v_and_b32_e32 v69, 0xffff0000, v69
	v_add_f32_e32 v1, 1.0, v1
	v_rcp_f32_e32 v72, v1
	v_mul_f32_e32 v1, 0xbfb8aa3b, v68
	v_exp_f32_e32 v1, v1
	v_and_b32_e32 v77, 0xffff0000, v64
	v_lshlrev_b32_e32 v79, 16, v64
	v_lshlrev_b32_e32 v64, 16, v63
	v_add_f32_e32 v1, 1.0, v1
	v_rcp_f32_e32 v74, v1
	v_mul_f32_e32 v1, 0xbfb8aa3b, v71
	v_exp_f32_e32 v1, v1
	v_and_b32_e32 v76, 0xffff0000, v62
	v_lshlrev_b32_e32 v78, 16, v62
	v_pk_fma_f32 v[76:77], v[14:15], v[78:79], v[76:77]
	v_add_f32_e32 v1, 1.0, v1
	v_rcp_f32_e32 v73, v1
	v_mul_f32_e32 v1, 0xbfb8aa3b, v69
	v_exp_f32_e32 v1, v1
	v_pk_mul_f32 v[70:71], v[72:73], v[70:71]
	v_and_b32_e32 v73, 0xffff0000, v65
	v_add_f32_e32 v1, 1.0, v1
	v_rcp_f32_e32 v75, v1
	v_and_b32_e32 v72, 0xffff0000, v63
	v_lshlrev_b32_e32 v65, 16, v65
	v_pk_fma_f32 v[62:63], v[8:9], v[64:65], v[72:73]
	v_pk_mul_f32 v[64:65], v[74:75], v[68:69]
	v_pk_mul_f32 v[70:71], v[76:77], v[70:71]
	v_pk_mul_f32 v[62:63], v[62:63], v[64:65]
	s_nop 0
	v_cvt_pk_bf16_f32 v65, v71, v63
	v_cvt_pk_bf16_f32 v63, v7, v67
	v_cvt_pk_bf16_f32 v64, v70, v62
	v_cvt_pk_bf16_f32 v62, v6, v66
	v_lshlrev_b32_e32 v6, 16, v54
	v_mul_f32_e32 v1, 0xbfb8aa3b, v6
	v_exp_f32_e32 v1, v1
	v_and_b32_e32 v54, 0xffff0000, v54
	v_add_f32_e32 v1, 1.0, v1
	global_store_dwordx4 v[114:115], v[62:65], off
	v_lshlrev_b32_e32 v7, 16, v55
	v_and_b32_e32 v55, 0xffff0000, v55
	v_rcp_f32_e32 v62, v1
	v_mul_f32_e32 v1, 0xbfb8aa3b, v54
	v_exp_f32_e32 v1, v1
	v_and_b32_e32 v67, 0xffff0000, v60
	v_lshlrev_b32_e32 v69, 16, v60
	v_lshlrev_b32_e32 v60, 16, v59
	v_add_f32_e32 v1, 1.0, v1
	v_rcp_f32_e32 v64, v1
	v_mul_f32_e32 v1, 0xbfb8aa3b, v7
	v_exp_f32_e32 v1, v1
	v_and_b32_e32 v66, 0xffff0000, v58
	v_lshlrev_b32_e32 v68, 16, v58
	v_pk_fma_f32 v[66:67], v[102:103], v[68:69], v[66:67]
	v_add_f32_e32 v1, 1.0, v1
	v_rcp_f32_e32 v63, v1
	v_mul_f32_e32 v1, 0xbfb8aa3b, v55
	v_exp_f32_e32 v1, v1
	v_pk_mul_f32 v[6:7], v[62:63], v[6:7]
	v_and_b32_e32 v63, 0xffff0000, v61
	v_add_f32_e32 v1, 1.0, v1
	v_rcp_f32_e32 v65, v1
	v_and_b32_e32 v62, 0xffff0000, v59
	v_lshlrev_b32_e32 v61, 16, v61
	v_pk_fma_f32 v[58:59], v[16:17], v[60:61], v[62:63]
	v_pk_mul_f32 v[54:55], v[64:65], v[54:55]
	v_pk_mul_f32 v[6:7], v[66:67], v[6:7]
	v_pk_mul_f32 v[54:55], v[58:59], v[54:55]
	v_lshlrev_b32_e32 v58, 16, v56
	v_mul_f32_e32 v1, 0xbfb8aa3b, v58
	v_exp_f32_e32 v1, v1
	v_and_b32_e32 v56, 0xffff0000, v56
	v_lshlrev_b32_e32 v59, 16, v57
	v_and_b32_e32 v57, 0xffff0000, v57
	v_add_f32_e32 v1, 1.0, v1
	v_rcp_f32_e32 v60, v1
	v_mul_f32_e32 v1, 0xbfb8aa3b, v56
	v_exp_f32_e32 v1, v1
	v_and_b32_e32 v65, 0xffff0000, v52
	v_lshlrev_b32_e32 v67, 16, v52
	v_lshlrev_b32_e32 v52, 16, v51
	v_add_f32_e32 v1, 1.0, v1
	v_rcp_f32_e32 v62, v1
	v_mul_f32_e32 v1, 0xbfb8aa3b, v59
	v_exp_f32_e32 v1, v1
	v_and_b32_e32 v64, 0xffff0000, v50
	v_lshlrev_b32_e32 v66, 16, v50
	v_pk_fma_f32 v[64:65], v[14:15], v[66:67], v[64:65]
	v_add_f32_e32 v1, 1.0, v1
	v_rcp_f32_e32 v61, v1
	v_mul_f32_e32 v1, 0xbfb8aa3b, v57
	v_exp_f32_e32 v1, v1
	v_pk_mul_f32 v[58:59], v[60:61], v[58:59]
	v_and_b32_e32 v61, 0xffff0000, v53
	v_add_f32_e32 v1, 1.0, v1
	v_rcp_f32_e32 v63, v1
	v_and_b32_e32 v60, 0xffff0000, v51
	v_lshlrev_b32_e32 v53, 16, v53
	v_pk_fma_f32 v[50:51], v[8:9], v[52:53], v[60:61]
	v_pk_mul_f32 v[52:53], v[62:63], v[56:57]
	v_pk_mul_f32 v[58:59], v[64:65], v[58:59]
	v_pk_mul_f32 v[50:51], v[50:51], v[52:53]
	s_nop 0
	v_cvt_pk_bf16_f32 v53, v59, v51
	v_cvt_pk_bf16_f32 v51, v7, v55
	v_cvt_pk_bf16_f32 v52, v58, v50
	v_cvt_pk_bf16_f32 v50, v6, v54
	v_lshlrev_b32_e32 v6, 16, v42
	v_mul_f32_e32 v1, 0xbfb8aa3b, v6
	v_exp_f32_e32 v1, v1
	v_and_b32_e32 v42, 0xffff0000, v42
	v_add_f32_e32 v1, 1.0, v1
	global_store_dwordx4 v[112:113], v[50:53], off
	v_lshlrev_b32_e32 v7, 16, v43
	v_and_b32_e32 v43, 0xffff0000, v43
	v_rcp_f32_e32 v50, v1
	v_mul_f32_e32 v1, 0xbfb8aa3b, v42
	v_exp_f32_e32 v1, v1
	v_and_b32_e32 v55, 0xffff0000, v48
	v_lshlrev_b32_e32 v57, 16, v48
	v_lshlrev_b32_e32 v48, 16, v47
	v_add_f32_e32 v1, 1.0, v1
	v_rcp_f32_e32 v52, v1
	v_mul_f32_e32 v1, 0xbfb8aa3b, v7
	v_exp_f32_e32 v1, v1
	v_and_b32_e32 v54, 0xffff0000, v46
	v_lshlrev_b32_e32 v56, 16, v46
	v_pk_fma_f32 v[54:55], v[102:103], v[56:57], v[54:55]
	v_add_f32_e32 v1, 1.0, v1
	v_rcp_f32_e32 v51, v1
	v_mul_f32_e32 v1, 0xbfb8aa3b, v43
	v_exp_f32_e32 v1, v1
	v_pk_mul_f32 v[6:7], v[50:51], v[6:7]
	v_and_b32_e32 v51, 0xffff0000, v49
	v_add_f32_e32 v1, 1.0, v1
	v_rcp_f32_e32 v53, v1
	v_and_b32_e32 v50, 0xffff0000, v47
	v_lshlrev_b32_e32 v49, 16, v49
	v_pk_fma_f32 v[46:47], v[16:17], v[48:49], v[50:51]
	v_pk_mul_f32 v[42:43], v[52:53], v[42:43]
	v_pk_mul_f32 v[6:7], v[54:55], v[6:7]
	v_pk_mul_f32 v[42:43], v[46:47], v[42:43]
	v_lshlrev_b32_e32 v46, 16, v44
	v_mul_f32_e32 v1, 0xbfb8aa3b, v46
	v_exp_f32_e32 v1, v1
	v_and_b32_e32 v44, 0xffff0000, v44
	v_lshlrev_b32_e32 v47, 16, v45
	v_and_b32_e32 v45, 0xffff0000, v45
	v_add_f32_e32 v1, 1.0, v1
	v_rcp_f32_e32 v48, v1
	v_mul_f32_e32 v1, 0xbfb8aa3b, v44
	v_exp_f32_e32 v1, v1
	v_and_b32_e32 v53, 0xffff0000, v40
	v_lshlrev_b32_e32 v55, 16, v40
	v_lshlrev_b32_e32 v40, 16, v39
	v_add_f32_e32 v1, 1.0, v1
	v_rcp_f32_e32 v50, v1
	v_mul_f32_e32 v1, 0xbfb8aa3b, v47
	v_exp_f32_e32 v1, v1
	v_and_b32_e32 v52, 0xffff0000, v38
	v_lshlrev_b32_e32 v54, 16, v38
	v_pk_fma_f32 v[52:53], v[14:15], v[54:55], v[52:53]
	v_add_f32_e32 v1, 1.0, v1
	v_rcp_f32_e32 v49, v1
	v_mul_f32_e32 v1, 0xbfb8aa3b, v45
	v_exp_f32_e32 v1, v1
	v_pk_mul_f32 v[46:47], v[48:49], v[46:47]
	v_and_b32_e32 v49, 0xffff0000, v41
	v_add_f32_e32 v1, 1.0, v1
	v_rcp_f32_e32 v51, v1
	v_and_b32_e32 v48, 0xffff0000, v39
	v_lshlrev_b32_e32 v41, 16, v41
	v_pk_fma_f32 v[38:39], v[8:9], v[40:41], v[48:49]
	v_pk_mul_f32 v[40:41], v[50:51], v[44:45]
	v_pk_mul_f32 v[46:47], v[52:53], v[46:47]
	v_pk_mul_f32 v[38:39], v[38:39], v[40:41]
	s_nop 0
	v_cvt_pk_bf16_f32 v41, v47, v39
	v_cvt_pk_bf16_f32 v39, v7, v43
	v_cvt_pk_bf16_f32 v40, v46, v38
	v_cvt_pk_bf16_f32 v38, v6, v42
	v_lshlrev_b32_e32 v6, 16, v30
	v_mul_f32_e32 v1, 0xbfb8aa3b, v6
	v_exp_f32_e32 v1, v1
	v_and_b32_e32 v30, 0xffff0000, v30
	v_add_f32_e32 v1, 1.0, v1
	global_store_dwordx4 v[110:111], v[38:41], off
	v_lshlrev_b32_e32 v7, 16, v31
	v_and_b32_e32 v31, 0xffff0000, v31
	v_rcp_f32_e32 v38, v1
	v_mul_f32_e32 v1, 0xbfb8aa3b, v30
	v_exp_f32_e32 v1, v1
	v_and_b32_e32 v43, 0xffff0000, v36
	v_lshlrev_b32_e32 v45, 16, v36
	v_lshlrev_b32_e32 v36, 16, v35
	v_add_f32_e32 v1, 1.0, v1
	v_rcp_f32_e32 v40, v1
	v_mul_f32_e32 v1, 0xbfb8aa3b, v7
	v_exp_f32_e32 v1, v1
	v_and_b32_e32 v42, 0xffff0000, v34
	v_lshlrev_b32_e32 v44, 16, v34
	v_pk_fma_f32 v[42:43], v[102:103], v[44:45], v[42:43]
	v_add_f32_e32 v1, 1.0, v1
	v_rcp_f32_e32 v39, v1
	v_mul_f32_e32 v1, 0xbfb8aa3b, v31
	v_exp_f32_e32 v1, v1
	v_pk_mul_f32 v[6:7], v[38:39], v[6:7]
	v_and_b32_e32 v39, 0xffff0000, v37
	v_add_f32_e32 v1, 1.0, v1
	v_rcp_f32_e32 v41, v1
	v_and_b32_e32 v38, 0xffff0000, v35
	v_lshlrev_b32_e32 v37, 16, v37
	v_pk_fma_f32 v[34:35], v[16:17], v[36:37], v[38:39]
	v_pk_mul_f32 v[30:31], v[40:41], v[30:31]
	v_pk_mul_f32 v[6:7], v[42:43], v[6:7]
	v_pk_mul_f32 v[30:31], v[34:35], v[30:31]
	v_lshlrev_b32_e32 v34, 16, v32
	v_mul_f32_e32 v1, 0xbfb8aa3b, v34
	v_exp_f32_e32 v1, v1
	v_and_b32_e32 v32, 0xffff0000, v32
	v_lshlrev_b32_e32 v35, 16, v33
	v_and_b32_e32 v33, 0xffff0000, v33
	v_add_f32_e32 v1, 1.0, v1
	v_rcp_f32_e32 v36, v1
	v_mul_f32_e32 v1, 0xbfb8aa3b, v32
	v_exp_f32_e32 v1, v1
	v_and_b32_e32 v41, 0xffff0000, v28
	v_lshlrev_b32_e32 v43, 16, v28
	v_lshlrev_b32_e32 v28, 16, v27
	v_add_f32_e32 v1, 1.0, v1
	v_rcp_f32_e32 v38, v1
	v_mul_f32_e32 v1, 0xbfb8aa3b, v35
	v_exp_f32_e32 v1, v1
	v_and_b32_e32 v40, 0xffff0000, v26
	v_lshlrev_b32_e32 v42, 16, v26
	v_pk_fma_f32 v[40:41], v[14:15], v[42:43], v[40:41]
	v_add_f32_e32 v1, 1.0, v1
	v_rcp_f32_e32 v37, v1
	v_mul_f32_e32 v1, 0xbfb8aa3b, v33
	v_exp_f32_e32 v1, v1
	v_pk_mul_f32 v[34:35], v[36:37], v[34:35]
	v_and_b32_e32 v37, 0xffff0000, v29
	v_add_f32_e32 v1, 1.0, v1
	v_rcp_f32_e32 v39, v1
	v_and_b32_e32 v36, 0xffff0000, v27
	v_lshlrev_b32_e32 v29, 16, v29
	v_pk_fma_f32 v[26:27], v[8:9], v[28:29], v[36:37]
	v_pk_mul_f32 v[28:29], v[38:39], v[32:33]
	v_pk_mul_f32 v[34:35], v[40:41], v[34:35]
	v_pk_mul_f32 v[26:27], v[26:27], v[28:29]
	s_nop 0
	v_cvt_pk_bf16_f32 v29, v35, v27
	v_cvt_pk_bf16_f32 v27, v7, v31
	v_cvt_pk_bf16_f32 v28, v34, v26
	v_cvt_pk_bf16_f32 v26, v6, v30
	s_waitcnt vmcnt(6)
	v_lshlrev_b32_e32 v6, 16, v18
	v_mul_f32_e32 v1, 0xbfb8aa3b, v6
	v_exp_f32_e32 v1, v1
	v_and_b32_e32 v18, 0xffff0000, v18
	v_add_f32_e32 v1, 1.0, v1
	global_store_dwordx4 v[108:109], v[26:29], off
	v_lshlrev_b32_e32 v7, 16, v19
	v_and_b32_e32 v19, 0xffff0000, v19
	v_rcp_f32_e32 v26, v1
	v_mul_f32_e32 v1, 0xbfb8aa3b, v18
	v_exp_f32_e32 v1, v1
	v_and_b32_e32 v31, 0xffff0000, v24
	v_lshlrev_b32_e32 v33, 16, v24
	v_lshlrev_b32_e32 v24, 16, v23
	v_add_f32_e32 v1, 1.0, v1
	v_rcp_f32_e32 v28, v1
	v_mul_f32_e32 v1, 0xbfb8aa3b, v7
	v_exp_f32_e32 v1, v1
	v_and_b32_e32 v30, 0xffff0000, v22
	v_lshlrev_b32_e32 v32, 16, v22
	v_pk_fma_f32 v[30:31], v[102:103], v[32:33], v[30:31]
	v_add_f32_e32 v1, 1.0, v1
	v_rcp_f32_e32 v27, v1
	v_mul_f32_e32 v1, 0xbfb8aa3b, v19
	v_exp_f32_e32 v1, v1
	v_pk_mul_f32 v[6:7], v[26:27], v[6:7]
	v_and_b32_e32 v27, 0xffff0000, v25
	v_add_f32_e32 v1, 1.0, v1
	v_rcp_f32_e32 v29, v1
	v_and_b32_e32 v26, 0xffff0000, v23
	v_lshlrev_b32_e32 v25, 16, v25
	v_pk_fma_f32 v[16:17], v[16:17], v[24:25], v[26:27]
	v_pk_mul_f32 v[18:19], v[28:29], v[18:19]
	v_and_b32_e32 v27, 0xffff0000, v12
	v_pk_mul_f32 v[16:17], v[16:17], v[18:19]
	v_lshlrev_b32_e32 v18, 16, v20
	v_mul_f32_e32 v1, 0xbfb8aa3b, v18
	v_exp_f32_e32 v1, v1
	v_and_b32_e32 v20, 0xffff0000, v20
	v_lshlrev_b32_e32 v19, 16, v21
	v_and_b32_e32 v21, 0xffff0000, v21
	v_add_f32_e32 v1, 1.0, v1
	v_rcp_f32_e32 v22, v1
	v_mul_f32_e32 v1, 0xbfb8aa3b, v20
	v_exp_f32_e32 v1, v1
	v_and_b32_e32 v26, 0xffff0000, v10
	v_lshlrev_b32_e32 v29, 16, v12
	v_lshlrev_b32_e32 v28, 16, v10
	v_add_f32_e32 v1, 1.0, v1
	v_rcp_f32_e32 v24, v1
	v_mul_f32_e32 v1, 0xbfb8aa3b, v19
	v_exp_f32_e32 v1, v1
	v_pk_fma_f32 v[14:15], v[14:15], v[28:29], v[26:27]
	v_lshlrev_b32_e32 v12, 16, v11
	v_pk_mul_f32 v[6:7], v[30:31], v[6:7]
	v_add_f32_e32 v1, 1.0, v1
	v_rcp_f32_e32 v23, v1
	v_mul_f32_e32 v1, 0xbfb8aa3b, v21
	v_exp_f32_e32 v1, v1
	v_pk_mul_f32 v[18:19], v[22:23], v[18:19]
	s_nop 0
	v_pk_mul_f32 v[14:15], v[14:15], v[18:19]
	v_add_f32_e32 v1, 1.0, v1
	v_rcp_f32_e32 v25, v1
	v_and_b32_e32 v19, 0xffff0000, v13
	v_and_b32_e32 v18, 0xffff0000, v11
	v_lshlrev_b32_e32 v13, 16, v13
	v_pk_fma_f32 v[8:9], v[8:9], v[12:13], v[18:19]
	v_pk_mul_f32 v[10:11], v[24:25], v[20:21]
	s_nop 0
	v_pk_mul_f32 v[8:9], v[8:9], v[10:11]
	v_cvt_pk_bf16_f32 v6, v6, v16
	v_cvt_pk_bf16_f32 v9, v15, v9
	v_cvt_pk_bf16_f32 v8, v14, v8
	v_cvt_pk_bf16_f32 v7, v7, v17
	global_store_dwordx4 v[106:107], v[6:9], off
	s_mov_b64 s[0:1], -1
	s_and_b64 vcc, exec, s[10:11]
	s_cbranch_vccnz .LBB0_393

.LBB0_460:
	v_mov_b32_e32 v38, v0
	v_readlane_b32 s0, v251, 55
	s_waitcnt lgkmcnt(0)
	v_lshlrev_b32_e32 v1, 3, v38
	v_and_b32_e32 v1, 0x1f8, v1
	v_lshlrev_b32_e32 v138, 1, v1
	v_add_u32_e32 v1, 0x200, v38
	v_readlane_b32 s1, v251, 56
	v_ashrrev_i32_e32 v40, 6, v1
	s_movk_i32 s4, 0x2800
	v_mov_b64_e32 v[30:31], s[0:1]
	v_add_u32_e32 v1, s88, v40
	v_mad_i64_i32 v[8:9], s[0:1], v1, s4, v[30:31]
	v_add_u32_e32 v1, 0x400, v38
	v_ashrrev_i32_e32 v41, 6, v1
	v_add_u32_e32 v1, s88, v41
	v_mad_i64_i32 v[14:15], s[0:1], v1, s4, v[30:31]
	v_add_u32_e32 v1, 0x600, v38
	v_ashrrev_i32_e32 v42, 6, v1
	v_add_u32_e32 v1, s88, v42
	v_mad_i64_i32 v[16:17], s[0:1], v1, s4, v[30:31]
	v_add_u32_e32 v1, 0x800, v38
	v_ashrrev_i32_e32 v43, 6, v1
	v_add_u32_e32 v1, s88, v43
	v_mad_i64_i32 v[22:23], s[0:1], v1, s4, v[30:31]
	v_add_u32_e32 v1, 0xa00, v38
	v_ashrrev_i32_e32 v44, 6, v1
	v_add_u32_e32 v1, s88, v44
	v_mad_i64_i32 v[24:25], s[0:1], v1, s4, v[30:31]
	v_add_u32_e32 v1, 0xc00, v38
	v_ashrrev_i32_e32 v45, 6, v1
	v_add_u32_e32 v1, s88, v45
	v_mad_i64_i32 v[32:33], s[0:1], v1, s4, v[30:31]
	v_add_u32_e32 v1, 0xe00, v38
	v_ashrrev_i32_e32 v39, 6, v38
	v_ashrrev_i32_e32 v46, 6, v1
	v_add_u32_e32 v6, s88, v39
	v_add_u32_e32 v1, s88, v46
	s_waitcnt lgkmcnt(0)
	v_mad_i64_i32 v[6:7], s[0:1], v6, s4, v[30:31]
	v_mad_i64_i32 v[30:31], s[0:1], v1, s4, v[30:31]
	v_lshl_add_u64 v[6:7], v[6:7], 0, v[138:139]
	v_lshl_add_u64 v[8:9], v[8:9], 0, v[138:139]
	v_lshl_add_u64 v[14:15], v[14:15], 0, v[138:139]
	v_lshl_add_u64 v[16:17], v[16:17], 0, v[138:139]
	v_lshl_add_u64 v[22:23], v[22:23], 0, v[138:139]
	v_lshl_add_u64 v[24:25], v[24:25], 0, v[138:139]
	v_lshl_add_u64 v[32:33], v[32:33], 0, v[138:139]
	v_lshl_add_u64 v[30:31], v[30:31], 0, v[138:139]
	s_nop 0
	s_nop 0
	s_nop 0
	s_nop 0
	s_nop 0
	s_nop 0
	s_nop 0
	s_nop 0
	s_nop 0
	s_nop 0
	s_nop 0
	s_nop 0
	s_nop 0
	s_nop 0
	s_nop 0
	s_movk_i32 s0, 0x410
	v_readfirstlane_b32 s20, v38
	v_cmp_gt_i32_e32 vcc, s0, v38
	s_and_saveexec_b64 s[0:1], vcc
	s_cbranch_execz .LBB0_463
	v_lshl_add_u32 v1, v38, 4, 0
	s_mov_b64 s[22:23], 0
	v_mov_b32_e32 v47, v38

.LBB0_463:
	s_or_b64 exec, exec, s[0:1]
	s_movk_i32 s0, 0x410
	v_mul_lo_u32 v39, v39, s0
	v_add3_u32 v39, 0, v39, v138
	s_waitcnt vmcnt(0)
	ds_write_b128 v39, v[162:165] offset:16640
	v_mul_lo_u32 v10, v40, s0
	v_add3_u32 v10, 0, v10, v138
	ds_write_b128 v10, v[166:169] offset:16640
	v_mul_lo_u32 v6, v41, s0
	v_add3_u32 v6, 0, v6, v138
	ds_write_b128 v6, v[170:173] offset:16640
	v_mul_lo_u32 v6, v42, s0
	v_add3_u32 v6, 0, v6, v138
	ds_write_b128 v6, v[174:177] offset:16640
	v_mul_lo_u32 v6, v43, s0
	v_add3_u32 v6, 0, v6, v138
	ds_write_b128 v6, v[178:181] offset:16640
	v_mul_lo_u32 v6, v44, s0
	v_add3_u32 v6, 0, v6, v138
	ds_write_b128 v6, v[182:185] offset:16640
	v_mul_lo_u32 v6, v45, s0
	v_add3_u32 v6, 0, v6, v138
	s_ashr_i32 s29, s28, 31
	ds_write_b128 v6, v[186:189] offset:16640
	v_mul_lo_u32 v6, v46, s0
	s_lshl_b64 s[0:1], s[28:29], 14
	v_readlane_b32 s4, v250, 35
	v_and_b32_e32 v1, 15, v38
	v_readlane_b32 s5, v250, 36
	s_add_u32 s0, s4, s0
	v_readlane_b32 s6, v254, 6
	v_add3_u32 v6, 0, v6, v138
	s_addc_u32 s1, s5, s1
	s_ashr_i32 s5, s20, 4
	v_lshlrev_b32_e32 v138, 5, v1
	v_readlane_b32 s7, v254, 7
	v_lshrrev_b32_e32 v47, 4, v38
	v_bfe_u32 v48, v38, 4, 2
	ds_write_b128 v6, v[190:193] offset:16640
	v_lshl_add_u64 v[6:7], s[6:7], 0, v[138:139]
	v_and_b32_e32 v8, 16, v38
	v_mov_b32_e32 v9, v139
	s_lshr_b32 s6, s5, 2
	s_and_b32 s4, s5, -4
	v_bfe_u32 v10, v47, 1, 1
	v_lshl_add_u64 v[148:149], v[6:7], 0, v[8:9]
	v_or_b32_e32 v147, 16, v1
	s_mul_i32 s5, s6, 0x1100
	v_mul_u32_u24_e32 v7, 0x44, v48
	v_sub_u32_e32 v6, v147, v10
	v_or_b32_e32 v239, s5, v7
	s_ashr_i32 s5, s4, 31
	v_mul_u32_u24_e32 v9, 0x410, v6
	v_lshlrev_b32_e32 v6, 8, v1
	s_lshl_b64 s[4:5], s[4:5], 12
	v_lshlrev_b32_e32 v138, 4, v48
	v_or3_b32 v6, s4, v6, v138
	v_mov_b32_e32 v7, s5
	v_readlane_b32 s4, v254, 57
	v_readlane_b32 s5, v254, 58
	s_lshl_b32 s7, s6, 8
	s_lshl_b32 s22, s6, 7
	v_lshl_add_u64 v[152:153], s[4:5], 0, v[6:7]
	s_lshl_b32 s4, s6, 6
	s_ashr_i32 s5, s4, 31
	s_lshl_b64 s[4:5], s[4:5], 2
	v_readlane_b32 s6, v254, 59
	s_add_u32 s4, s6, s4
	v_readlane_b32 s6, v254, 60
	s_addc_u32 s5, s6, s5
	v_lshlrev_b32_e32 v238, 3, v48
	v_lshlrev_b32_e32 v146, 2, v48
	v_mul_u32_u24_e32 v236, 0x410, v147
	v_mul_u32_u24_e32 v237, 0x410, v1
	v_lshl_add_u64 v[154:155], s[4:5], 0, v[138:139]
	v_readlane_b32 s4, v253, 3
	v_or_b32_e32 v150, s7, v10
	v_add_u32_e32 v240, v239, v1
	v_add3_u32 v241, v237, v238, 0
	v_add3_u32 v242, v236, v238, 0
	v_add3_u32 v243, v9, v8, s4
	v_or_b32_e32 v156, s7, v146
	s_mov_b32 s23, 0
	s_waitcnt lgkmcnt(0)
	s_barrier

.LBB0_484:
	v_mov_b32_e32 v1, v0
	s_barrier
	s_mov_b64 s[8:9], s[50:51]
	v_readfirstlane_b32 s89, v1
	s_ashr_i32 s22, s89, 6
	s_add_i32 s0, s22, s90
	s_ashr_i32 s1, s0, 31
	v_readlane_b32 s36, v252, 0
	s_lshl_b64 s[0:1], s[0:1], 2
	v_readlane_b32 s38, v252, 2
	v_readlane_b32 s39, v252, 3
	s_add_u32 s4, s38, s0
	v_readlane_b32 s40, v252, 4
	s_addc_u32 s5, s39, s1
	v_readlane_b32 s41, v252, 5
	s_add_u32 s0, s40, s0
	s_addc_u32 s1, s41, s1
	global_load_dword v8, v139, s[4:5]
	global_load_dword v6, v139, s[0:1]
	v_and_b32_e32 v137, 63, v1
	v_readlane_b32 s0, v250, 47
	v_readlane_b32 s1, v250, 48
	s_ashr_i32 s23, s22, 31
	v_or_b32_e32 v12, s88, v137
	v_ashrrev_i32_e32 v13, 31, v12
	v_lshlrev_b64 v[12:13], 7, v[12:13]
	v_lshl_add_u64 v[12:13], s[0:1], 0, v[12:13]
	v_lshl_add_u64 v[12:13], s[22:23], 2, v[12:13]
	global_load_dword v14, v[12:13], off
	v_and_b32_e32 v136, 64, v228
	v_cmp_eq_u32_e64 s[38:39], 0, v137
	v_readlane_b32 s37, v252, 1
	v_cmp_gt_u32_e64 s[36:37], 16, v137
	v_and_b32_e32 v122, 0x7f, v1
	v_writelane_b32 v253, s84, 51
	v_lshlrev_b32_e32 v138, 3, v122
	v_readlane_b32 s42, v252, 6
	v_readlane_b32 s43, v252, 7
	v_readlane_b32 s44, v252, 8
	v_readlane_b32 s45, v252, 9
	v_readlane_b32 s46, v252, 10
	v_readlane_b32 s47, v252, 11
	v_readlane_b32 s48, v252, 12
	v_readlane_b32 s49, v252, 13
	v_readlane_b32 s50, v252, 14
	v_readlane_b32 s51, v252, 15
	s_waitcnt vmcnt(0)
	v_mul_f32_e32 v7, 0x3fb8aa3b, v6
	v_fma_f32 v9, v6, s80, -v7
	v_rndne_f32_e32 v10, v7
	v_fmac_f32_e32 v9, 0x32a5705f, v6
	v_sub_f32_e32 v7, v7, v10
	v_add_f32_e32 v7, v7, v9
	v_exp_f32_e32 v7, v7
	v_cvt_i32_f32_e32 v9, v10
	v_cmp_ngt_f32_e32 vcc, s81, v6
	v_ldexp_f32 v7, v7, v9
	s_nop 0
	v_cndmask_b32_e32 v7, 0, v7, vcc
	v_cmp_nlt_f32_e32 vcc, s82, v6
	s_nop 0
	s_nop 0
	v_cndmask_b32_e32 v9, v231, v7, vcc
	v_cmp_lt_u32_e64 s[0:1], 63, v122
	s_waitcnt vmcnt(0)
	v_add_f32_e32 v6, v8, v14
	v_max_f32_e32 v7, 0, v6
	v_mul_f32_e64 v6, |v6|, s13
	v_exp_f32_e32 v6, v6
	v_add_u32_e32 v8, -1, v228
	v_cmp_lt_i32_e32 vcc, v8, v136
	v_add_f32_e32 v6, 1.0, v6
	v_log_f32_e32 v6, v6
	v_cndmask_b32_e32 v8, v8, v228, vcc
	v_lshlrev_b32_e32 v8, 2, v8
	v_fmac_f32_e32 v7, 0x3f317218, v6
	v_mul_f32_e64 v6, v7, -v9
	ds_bpermute_b32 v8, v8, v6
	s_waitcnt lgkmcnt(0)
	v_fma_f32 v8, v7, -v9, v8
	v_cndmask_b32_e64 v6, v8, v6, s[38:39]
	v_add_u32_e32 v8, -2, v228
	v_cmp_lt_i32_e32 vcc, v8, v136
	s_nop 1
	v_cndmask_b32_e32 v8, v8, v228, vcc
	v_lshlrev_b32_e32 v8, 2, v8
	ds_bpermute_b32 v8, v8, v6
	v_cmp_gt_u32_e32 vcc, 2, v137
	s_waitcnt lgkmcnt(0)
	v_add_f32_e32 v8, v6, v8
	v_cndmask_b32_e32 v6, v8, v6, vcc
	v_add_u32_e32 v8, -4, v228
	v_cmp_lt_i32_e32 vcc, v8, v136
	s_nop 1
	v_cndmask_b32_e32 v8, v8, v228, vcc
	v_lshlrev_b32_e32 v8, 2, v8
	ds_bpermute_b32 v8, v8, v6
	v_cmp_gt_u32_e32 vcc, 4, v137
	s_waitcnt lgkmcnt(0)
	v_add_f32_e32 v8, v6, v8
	v_cndmask_b32_e32 v6, v8, v6, vcc
	v_add_u32_e32 v8, -8, v228
	v_cmp_lt_i32_e32 vcc, v8, v136
	s_nop 1
	v_cndmask_b32_e32 v8, v8, v228, vcc
	v_lshlrev_b32_e32 v8, 2, v8
	ds_bpermute_b32 v8, v8, v6
	v_cmp_gt_u32_e32 vcc, 8, v137
	s_waitcnt lgkmcnt(0)
	v_add_f32_e32 v8, v6, v8
	v_cndmask_b32_e32 v6, v8, v6, vcc
	v_add_u32_e32 v8, -16, v228
	v_cmp_lt_i32_e32 vcc, v8, v136
	s_nop 1
	v_cndmask_b32_e32 v8, v8, v228, vcc
	v_lshlrev_b32_e32 v8, 2, v8
	ds_bpermute_b32 v8, v8, v6
	s_waitcnt lgkmcnt(0)
	v_add_f32_e32 v8, v6, v8
	v_cndmask_b32_e64 v6, v8, v6, s[36:37]
	v_subrev_u32_e32 v8, 32, v228
	v_cmp_lt_i32_e32 vcc, v8, v136
	s_nop 1
	v_cndmask_b32_e32 v8, v8, v228, vcc
	v_lshlrev_b32_e32 v8, 2, v8
	ds_bpermute_b32 v8, v8, v6
	v_cmp_gt_u32_e32 vcc, 32, v137
	s_waitcnt lgkmcnt(0)
	v_add_f32_e32 v8, v6, v8
	v_cndmask_b32_e32 v6, v8, v6, vcc
	v_lshl_add_u32 v8, v137, 3, s22
	v_lshl_add_u32 v8, v8, 2, 0
	v_add_u32_e32 v9, 0x21800, v8
	ds_write_b32 v9, v7
	v_add_u32_e32 v7, 0x22000, v8
	v_cmp_gt_u32_e32 vcc, 64, v122
	ds_write_b32 v7, v6
	s_waitcnt lgkmcnt(0)
	s_barrier
	s_and_saveexec_b64 s[4:5], vcc
	s_xor_b64 s[30:31], exec, s[4:5]
	v_lshlrev_b32_e32 v138, 3, v122
	v_add_u32_e32 v46, 0x1100, v138
	v_lshl_add_u32 v146, v122, 4, 0
	s_or_saveexec_b64 s[30:31], s[30:31]
	v_mov_b32_e32 v147, 0x208
	s_mov_b64 s[14:15], 0x1000
	s_mov_b64 s[42:43], 0x60
	s_mov_b64 s[50:51], s[8:9]
	s_xor_b64 exec, exec, s[30:31]
	s_cbranch_execz .LBB0_492
	s_movk_i32 s4, 0x5f
	v_cmp_lt_u32_e32 vcc, s4, v122
	s_and_saveexec_b64 s[4:5], vcc
	s_xor_b64 s[34:35], exec, s[4:5]
	s_add_i32 s4, 0, 0x10400
	v_lshl_add_u32 v6, v138, 1, s4
	v_add_u32_e32 v46, 0xb00, v138
	v_add_u32_e32 v146, 0xfffffa00, v6
	s_andn2_saveexec_b64 s[34:35], s[34:35]
	s_cbranch_execz .LBB0_491
	v_readlane_b32 s4, v253, 7
	v_add_u32_e32 v46, 0x1100, v138
	s_nop 0
	v_lshl_add_u32 v6, v138, 1, s4
	v_add_u32_e32 v146, 0xfffffc00, v6
